# first K-loop iteration peeled in all six GEMM loops with srcC=0 (removes 128 v_mov accumulator zeroing per tile per wave) on top of SGPR-base LDS-DMA addressing, combine batching, prologue readback pi
# speedup vs baseline: 1.0070x; 1.0070x over previous
; #define PG8_STAGE(bufoff, gbase, voff) do { _Pragma("unroll") for (int _i = 0; _i < 2; ++_i) \
;         __builtin_amdgcn_global_load_lds((const unsigned*)((const char*)(gbase) + (voff)[_i]), (PG8_LAS unsigned*)(lds + (bufoff) + ldsw + _i * 8192), 16, 0, 0); } while (0)
; #define PG8_LDA(dst, b, h) do { _Pragma("unroll") for (int m = 0; m < 4; ++m) _Pragma("unroll") for (int k = 0; k < 2; ++k) dst[m][k] = *(const PG8_LAS bf16x8*)(lds + PG8_SA(b, h) + aoff + m * 2048 + k * 1024); } while (0)
; #define PG8_LDB(dst, b, h) do { _Pragma("unroll") for (int n = 0; n < 2; ++n) _Pragma("unroll") for (int k = 0; k < 2; ++k) dst[n][k] = *(const PG8_LAS bf16x8*)(lds + PG8_SB(b, h) + boff + n * 2048 + k * 1024); } while (0)
; #define PG8_MMA(ai, bj, At, Bt) do { __builtin_amdgcn_s_setprio(1); _Pragma("unroll") for (int m = 0; m < 4; ++m) _Pragma("unroll") for (int n = 0; n < 2; ++n) _Pragma("unroll") for (int k = 0; k < 2; ++k) \
;         acc[ai][bj][m][n] = __builtin_amdgcn_mfma_f32_16x16x32_bf16(Bt[n][k], At[m][k], acc[ai][bj][m][n], 0, 0, 0); __builtin_amdgcn_s_setprio(0); } while (0)
; #define PG8_WAIT_V(n) asm volatile("s_waitcnt vmcnt(" #n ")" ::: "memory")
; template <class Epi, class Sched, bool ALIGN_EPI = false, bool SP2 = false>
; __device__ __forceinline__ void gemm_phase(PG8_LAS unsigned char* lds, const Gemm g, const Sched& S, const Epi& E) {
;     ...
;         const char* nA = has_next ? (const char*)g.A + (size_t)nxt.pm * tstep : cA; const char* nB = has_next ? (const char*)g.Bt + (size_t)nxt.pn * tstep : cB;
;         for (int t = 0; t < nt; t += 2) {
;             const bool last = (t == nt - 2);
;             const char* a1 = cA + (size_t)(t + 1) * kstep;
;             const char* a2 = last ? nA : cA + (size_t)(t + 2) * kstep; const char* b2 = last ? nB : cB + (size_t)(t + 2) * kstep;
;             const char* a3 = a2 + kstep; const char* b3 = b2 + kstep;
;             if (last && has_next) S.a_ready(nxt);
;             if constexpr (SP2) {
;             PG8_LDB(B0, 0, 0); PG8_LDB(B1, 0, 1); PG8_SCHED; PG8_LDA(At, 0, 0); PG8_STAGE(PG8_SA(1, 1), a1 + hstep, voffA);
;             PG8_WAIT_V(8); PG8_WAIT_L(0); PG8_BAR; PG8_MMA(0, 0, At, B0); PG8_MMA(0, 1, At, B1); PG8_BAR; PG8_SCHED;
;             PG8_LDA(At, 0, 1); PG8_STAGE(PG8_SB(0, 0), b2, voffB); PG8_STAGE(PG8_SB(0, 1), b2 + hstep, voffB); PG8_STAGE(PG8_SA(0, 0), a2, voffA);
.LBB0_84:
	s_ashr_i32 s11, s10, 31
	s_lshl_b64 s[12:13], s[10:11], 20
	s_add_u32 s12, s46, s12
	s_addc_u32 s13, s47, s13
	s_and_b64 s[14:15], s[2:3], exec
	s_cselect_b32 s11, s13, s19
	s_cselect_b32 s42, s12, s18
	s_ashr_i32 s9, s8, 31
	s_lshl_b64 s[14:15], s[8:9], 20
	v_readlane_b32 s9, v255, 30
	s_add_u32 s14, s9, s14
	v_readlane_b32 s9, v255, 31
	s_addc_u32 s15, s9, s15
	s_and_b64 s[22:23], s[2:3], exec
	s_cselect_b32 s9, s15, s21
	s_cselect_b32 s44, s14, s20
	s_add_u32 s18, s18, 0x80080
	s_addc_u32 s19, s19, 0
	s_add_u32 s45, s20, 0x100
	s_addc_u32 s50, s21, 0
	s_mov_b32 s51, -2
	s_add_u32 s20, s18, 0xfff80080
	s_addc_u32 s21, s19, -1
	s_add_i32 s56, 0, 0x10000
	s_cmp_eq_u32 s51, 28
	s_cselect_b32 s23, s11, s21
	s_cselect_b32 s22, s42, s20
	v_add_u32_e32 v150, s56, v153
	s_cselect_b32 s21, s9, s50
	s_cselect_b32 s20, s44, s45
	s_add_i32 s63, 0, 0x14000
	ds_read_b128 v[184:187], v150
	ds_read_b128 v[188:191], v150 offset:1024
	ds_read_b128 v[192:195], v150 offset:2048
	ds_read_b128 v[196:199], v150 offset:3072
	v_add_u32_e32 v150, s63, v153
	ds_read_b128 v[200:203], v150
	ds_read_b128 v[204:207], v150 offset:1024
	ds_read_b128 v[208:211], v150 offset:2048
	ds_read_b128 v[212:215], v150 offset:3072
	s_add_i32 m0, s27, 0xc000
	ds_read_b128 v[216:219], v155
	ds_read_b128 v[220:223], v155 offset:1024
	ds_read_b128 v[224:227], v155 offset:2048
	ds_read_b128 v[228:231], v155 offset:3072
	ds_read_b128 v[232:235], v155 offset:4096
	ds_read_b128 v[236:239], v155 offset:5120
	ds_read_b128 v[240:243], v155 offset:6144
	ds_read_b128 v[244:247], v155 offset:7168
	global_load_lds_dwordx4 v136, s[18:19]
	s_add_i32 m0, s27, 0xe000
	s_nop 0
	global_load_lds_dwordx4 v138, s[18:19]
	s_waitcnt vmcnt(8)
	s_waitcnt lgkmcnt(0)
	s_barrier
	s_setprio 1
	s_waitcnt lgkmcnt(0)
	v_mfma_f32_16x16x32_bf16 v[128:131], v[184:187], v[216:219], 0
	v_mfma_f32_16x16x32_bf16 v[120:123], v[192:195], v[216:219], 0
	v_mfma_f32_16x16x32_bf16 v[112:115], v[184:187], v[224:227], 0
	v_mfma_f32_16x16x32_bf16 v[104:107], v[192:195], v[224:227], 0
	v_mfma_f32_16x16x32_bf16 v[96:99], v[184:187], v[232:235], 0
	v_mfma_f32_16x16x32_bf16 v[88:91], v[192:195], v[232:235], 0
	v_mfma_f32_16x16x32_bf16 v[80:83], v[184:187], v[240:243], 0
	v_mfma_f32_16x16x32_bf16 v[72:75], v[192:195], v[240:243], 0
	v_mfma_f32_16x16x32_bf16 v[128:131], v[188:191], v[220:223], v[128:131]
	v_mfma_f32_16x16x32_bf16 v[120:123], v[196:199], v[220:223], v[120:123]
	v_mfma_f32_16x16x32_bf16 v[112:115], v[188:191], v[228:231], v[112:115]
	v_mfma_f32_16x16x32_bf16 v[104:107], v[196:199], v[228:231], v[104:107]
	v_mfma_f32_16x16x32_bf16 v[96:99], v[188:191], v[236:239], v[96:99]
	v_mfma_f32_16x16x32_bf16 v[88:91], v[196:199], v[236:239], v[88:91]
	v_mfma_f32_16x16x32_bf16 v[80:83], v[188:191], v[244:247], v[80:83]
	v_mfma_f32_16x16x32_bf16 v[72:75], v[196:199], v[244:247], v[72:75]
	s_setprio 0
	s_setprio 1
	v_mfma_f32_16x16x32_bf16 v[124:127], v[200:203], v[216:219], 0
	v_mfma_f32_16x16x32_bf16 v[116:119], v[208:211], v[216:219], 0
	v_mfma_f32_16x16x32_bf16 v[108:111], v[200:203], v[224:227], 0
	v_mfma_f32_16x16x32_bf16 v[100:103], v[208:211], v[224:227], 0
	v_mfma_f32_16x16x32_bf16 v[92:95], v[200:203], v[232:235], 0
	v_mfma_f32_16x16x32_bf16 v[84:87], v[208:211], v[232:235], 0
	v_mfma_f32_16x16x32_bf16 v[76:79], v[200:203], v[240:243], 0
	v_mfma_f32_16x16x32_bf16 v[68:71], v[208:211], v[240:243], 0
	v_mfma_f32_16x16x32_bf16 v[124:127], v[204:207], v[220:223], v[124:127]
	v_mfma_f32_16x16x32_bf16 v[116:119], v[212:215], v[220:223], v[116:119]
	v_mfma_f32_16x16x32_bf16 v[108:111], v[204:207], v[228:231], v[108:111]
	v_mfma_f32_16x16x32_bf16 v[100:103], v[212:215], v[228:231], v[100:103]
	v_mfma_f32_16x16x32_bf16 v[92:95], v[204:207], v[236:239], v[92:95]
	v_mfma_f32_16x16x32_bf16 v[84:87], v[212:215], v[236:239], v[84:87]
	v_mfma_f32_16x16x32_bf16 v[76:79], v[204:207], v[244:247], v[76:79]
	v_mfma_f32_16x16x32_bf16 v[68:71], v[212:215], v[244:247], v[68:71]
	s_setprio 0
	s_barrier
	s_add_i32 s56, s56, s25
	s_mov_b32 m0, s56
	ds_read_b128 v[216:219], v155 offset:16384
	ds_read_b128 v[220:223], v155 offset:17408
	ds_read_b128 v[224:227], v155 offset:18432
	ds_read_b128 v[228:231], v155 offset:19456
	ds_read_b128 v[232:235], v155 offset:20480
	ds_read_b128 v[236:239], v155 offset:21504
	ds_read_b128 v[240:243], v155 offset:22528
	ds_read_b128 v[244:247], v155 offset:23552
	global_load_lds_dwordx4 v2, s[20:21]
	s_add_i32 m0, s56, 0x2000
	s_add_u32 s56, s20, 0x80000
	s_addc_u32 s57, s21, 0
	s_add_i32 s63, s63, s25
	global_load_lds_dwordx4 v0, s[20:21]
	s_mov_b32 m0, s63
	v_lshl_add_u64 v[252:253], s[22:23], 0, v[132:133]
	global_load_lds_dwordx4 v2, s[56:57]
	s_add_i32 m0, s63, 0x2000
	s_nop 0
	global_load_lds_dwordx4 v0, s[56:57]
	v_lshl_add_u64 v[250:251], s[22:23], 0, v[134:135]
	s_mov_b32 m0, s27
	s_nop 0
	global_load_lds_dwordx4 v[250:251], off
	s_mov_b32 m0, s28
	s_nop 0
	global_load_lds_dwordx4 v[252:253], off
	s_waitcnt vmcnt(8)
	s_waitcnt lgkmcnt(0)
	s_barrier
; #define PG8_STAGE(bufoff, gbase, voff) do { _Pragma("unroll") for (int _i = 0; _i < 2; ++_i) \
;         __builtin_amdgcn_global_load_lds((const unsigned*)((const char*)(gbase) + (voff)[_i]), (PG8_LAS unsigned*)(lds + (bufoff) + ldsw + _i * 8192), 16, 0, 0); } while (0)
; #define PG8_LDA(dst, b, h) do { _Pragma("unroll") for (int m = 0; m < 4; ++m) _Pragma("unroll") for (int k = 0; k < 2; ++k) dst[m][k] = *(const PG8_LAS bf16x8*)(lds + PG8_SA(b, h) + aoff + m * 2048 + k * 1024); } while (0)
; #define PG8_LDB(dst, b, h) do { _Pragma("unroll") for (int n = 0; n < 2; ++n) _Pragma("unroll") for (int k = 0; k < 2; ++k) dst[n][k] = *(const PG8_LAS bf16x8*)(lds + PG8_SB(b, h) + boff + n * 2048 + k * 1024); } while (0)
; #define PG8_MMA(ai, bj, At, Bt) do { __builtin_amdgcn_s_setprio(1); _Pragma("unroll") for (int m = 0; m < 4; ++m) _Pragma("unroll") for (int n = 0; n < 2; ++n) _Pragma("unroll") for (int k = 0; k < 2; ++k) \
;         acc[ai][bj][m][n] = __builtin_amdgcn_mfma_f32_16x16x32_bf16(Bt[n][k], At[m][k], acc[ai][bj][m][n], 0, 0, 0); __builtin_amdgcn_s_setprio(0); } while (0)
; #define PG8_WAIT_V(n) asm volatile("s_waitcnt vmcnt(" #n ")" ::: "memory")
; #define PG8_WAIT_L(n) asm volatile("s_waitcnt lgkmcnt(" #n ")" ::: "memory")
; #define PG8_BAR __builtin_amdgcn_s_barrier()
; #define PG8_SCHED __builtin_amdgcn_sched_barrier(0)
; template <class Epi, class Sched, bool ALIGN_EPI = false, bool SP2 = false>
; __device__ __forceinline__ void gemm_phase(PG8_LAS unsigned char* lds, const Gemm g, const Sched& S, const Epi& E) {
;     ...
;             PG8_WAIT_V(8); PG8_WAIT_L(0); PG8_BAR; PG8_MMA(1, 0, At, B0); PG8_MMA(1, 1, At, B1); PG8_BAR; PG8_SCHED;
;             PG8_LDB(B0, 1, 0); PG8_LDB(B1, 1, 1); PG8_SCHED; PG8_LDA(At, 1, 0); PG8_STAGE(PG8_SA(0, 1), a2 + hstep, voffA);
;             PG8_WAIT_V(8); PG8_WAIT_L(0); PG8_BAR; PG8_MMA(0, 0, At, B0); PG8_MMA(0, 1, At, B1); PG8_BAR; PG8_SCHED;
	s_setprio 1
	s_waitcnt lgkmcnt(0)
	v_mfma_f32_16x16x32_bf16 v[64:67], v[184:187], v[216:219], 0
	v_mfma_f32_16x16x32_bf16 v[56:59], v[192:195], v[216:219], 0
	v_mfma_f32_16x16x32_bf16 v[48:51], v[184:187], v[224:227], 0
	v_mfma_f32_16x16x32_bf16 v[40:43], v[192:195], v[224:227], 0
	v_mfma_f32_16x16x32_bf16 v[32:35], v[184:187], v[232:235], 0
	v_mfma_f32_16x16x32_bf16 v[24:27], v[192:195], v[232:235], 0
	v_mfma_f32_16x16x32_bf16 v[16:19], v[184:187], v[240:243], 0
	v_mfma_f32_16x16x32_bf16 v[8:11], v[192:195], v[240:243], 0
	v_mfma_f32_16x16x32_bf16 v[64:67], v[188:191], v[220:223], v[64:67]
	v_mfma_f32_16x16x32_bf16 v[56:59], v[196:199], v[220:223], v[56:59]
	v_mfma_f32_16x16x32_bf16 v[48:51], v[188:191], v[228:231], v[48:51]
	v_mfma_f32_16x16x32_bf16 v[40:43], v[196:199], v[228:231], v[40:43]
	v_mfma_f32_16x16x32_bf16 v[32:35], v[188:191], v[236:239], v[32:35]
	v_mfma_f32_16x16x32_bf16 v[24:27], v[196:199], v[236:239], v[24:27]
	v_mfma_f32_16x16x32_bf16 v[16:19], v[188:191], v[244:247], v[16:19]
	v_mfma_f32_16x16x32_bf16 v[8:11], v[196:199], v[244:247], v[8:11]
	s_setprio 0
	s_setprio 1
	v_mfma_f32_16x16x32_bf16 v[60:63], v[200:203], v[216:219], 0
	v_mfma_f32_16x16x32_bf16 v[52:55], v[208:211], v[216:219], 0
	v_mfma_f32_16x16x32_bf16 v[44:47], v[200:203], v[224:227], 0
	v_mfma_f32_16x16x32_bf16 v[36:39], v[208:211], v[224:227], 0
	v_mfma_f32_16x16x32_bf16 v[28:31], v[200:203], v[232:235], 0
	v_mfma_f32_16x16x32_bf16 v[20:23], v[208:211], v[232:235], 0
	v_mfma_f32_16x16x32_bf16 v[12:15], v[200:203], v[240:243], 0
	v_mfma_f32_16x16x32_bf16 v[4:7], v[208:211], v[240:243], 0
	v_mfma_f32_16x16x32_bf16 v[60:63], v[204:207], v[220:223], v[60:63]
	v_mfma_f32_16x16x32_bf16 v[52:55], v[212:215], v[220:223], v[52:55]
	v_mfma_f32_16x16x32_bf16 v[44:47], v[204:207], v[228:231], v[44:47]
	v_mfma_f32_16x16x32_bf16 v[36:39], v[212:215], v[228:231], v[36:39]
	v_mfma_f32_16x16x32_bf16 v[28:31], v[204:207], v[236:239], v[28:31]
	v_mfma_f32_16x16x32_bf16 v[20:23], v[212:215], v[236:239], v[20:23]
	v_mfma_f32_16x16x32_bf16 v[12:15], v[204:207], v[244:247], v[12:15]
	v_mfma_f32_16x16x32_bf16 v[4:7], v[212:215], v[244:247], v[4:7]
	s_setprio 0
	s_barrier
	s_add_i32 s56, 0, 0x18000
	v_add_u32_e32 v161, s56, v153
	s_add_i32 s57, 0, 0x1c000
	ds_read_b128 v[184:187], v161
	ds_read_b128 v[188:191], v161 offset:1024
	ds_read_b128 v[192:195], v161 offset:2048
	ds_read_b128 v[196:199], v161 offset:3072
	v_add_u32_e32 v161, s57, v153
	ds_read_b128 v[200:203], v161
	ds_read_b128 v[204:207], v161 offset:1024
	ds_read_b128 v[208:211], v161 offset:2048
	ds_read_b128 v[212:215], v161 offset:3072
	s_add_u32 s22, s22, 0x80000
	s_addc_u32 s23, s23, 0
	s_mov_b32 m0, s29
	ds_read_b128 v[216:219], v155 offset:32768
	ds_read_b128 v[220:223], v155 offset:33792
	ds_read_b128 v[224:227], v155 offset:34816
	ds_read_b128 v[228:231], v155 offset:35840
	ds_read_b128 v[232:235], v155 offset:36864
	ds_read_b128 v[236:239], v155 offset:37888
	ds_read_b128 v[240:243], v155 offset:38912
	ds_read_b128 v[244:247], v155 offset:39936
	global_load_lds_dwordx4 v134, s[22:23]
	s_mov_b32 m0, s30
	s_nop 0
	global_load_lds_dwordx4 v132, s[22:23]
	s_waitcnt vmcnt(8)
	s_waitcnt lgkmcnt(0)
	s_barrier
	s_setprio 1
	s_waitcnt lgkmcnt(0)
	v_mfma_f32_16x16x32_bf16 v[128:131], v[184:187], v[216:219], v[128:131]
	v_mfma_f32_16x16x32_bf16 v[120:123], v[192:195], v[216:219], v[120:123]
	v_mfma_f32_16x16x32_bf16 v[112:115], v[184:187], v[224:227], v[112:115]
	v_mfma_f32_16x16x32_bf16 v[104:107], v[192:195], v[224:227], v[104:107]
	v_mfma_f32_16x16x32_bf16 v[96:99], v[184:187], v[232:235], v[96:99]
	v_mfma_f32_16x16x32_bf16 v[88:91], v[192:195], v[232:235], v[88:91]
	v_mfma_f32_16x16x32_bf16 v[80:83], v[184:187], v[240:243], v[80:83]
	v_mfma_f32_16x16x32_bf16 v[72:75], v[192:195], v[240:243], v[72:75]
	v_mfma_f32_16x16x32_bf16 v[128:131], v[188:191], v[220:223], v[128:131]
	v_mfma_f32_16x16x32_bf16 v[120:123], v[196:199], v[220:223], v[120:123]
	v_mfma_f32_16x16x32_bf16 v[112:115], v[188:191], v[228:231], v[112:115]
	v_mfma_f32_16x16x32_bf16 v[104:107], v[196:199], v[228:231], v[104:107]
	v_mfma_f32_16x16x32_bf16 v[96:99], v[188:191], v[236:239], v[96:99]
	v_mfma_f32_16x16x32_bf16 v[88:91], v[196:199], v[236:239], v[88:91]
	v_mfma_f32_16x16x32_bf16 v[80:83], v[188:191], v[244:247], v[80:83]
	v_mfma_f32_16x16x32_bf16 v[72:75], v[196:199], v[244:247], v[72:75]
	s_setprio 0
	s_setprio 1
	v_mfma_f32_16x16x32_bf16 v[124:127], v[200:203], v[216:219], v[124:127]
	v_mfma_f32_16x16x32_bf16 v[116:119], v[208:211], v[216:219], v[116:119]
	v_mfma_f32_16x16x32_bf16 v[108:111], v[200:203], v[224:227], v[108:111]
	v_mfma_f32_16x16x32_bf16 v[100:103], v[208:211], v[224:227], v[100:103]
	v_mfma_f32_16x16x32_bf16 v[92:95], v[200:203], v[232:235], v[92:95]
	v_mfma_f32_16x16x32_bf16 v[84:87], v[208:211], v[232:235], v[84:87]
	v_mfma_f32_16x16x32_bf16 v[76:79], v[200:203], v[240:243], v[76:79]
	v_mfma_f32_16x16x32_bf16 v[68:71], v[208:211], v[240:243], v[68:71]
	v_mfma_f32_16x16x32_bf16 v[124:127], v[204:207], v[220:223], v[124:127]
	v_mfma_f32_16x16x32_bf16 v[116:119], v[212:215], v[220:223], v[116:119]
	v_mfma_f32_16x16x32_bf16 v[108:111], v[204:207], v[228:231], v[108:111]
	v_mfma_f32_16x16x32_bf16 v[100:103], v[212:215], v[228:231], v[100:103]
	v_mfma_f32_16x16x32_bf16 v[92:95], v[204:207], v[236:239], v[92:95]
	v_mfma_f32_16x16x32_bf16 v[84:87], v[212:215], v[236:239], v[84:87]
	v_mfma_f32_16x16x32_bf16 v[76:79], v[204:207], v[244:247], v[76:79]
	v_mfma_f32_16x16x32_bf16 v[68:71], v[212:215], v[244:247], v[68:71]
	s_setprio 0
	s_barrier
; #define PG8_STAGE(bufoff, gbase, voff) do { _Pragma("unroll") for (int _i = 0; _i < 2; ++_i) \
;         __builtin_amdgcn_global_load_lds((const unsigned*)((const char*)(gbase) + (voff)[_i]), (PG8_LAS unsigned*)(lds + (bufoff) + ldsw + _i * 8192), 16, 0, 0); } while (0)
; #define PG8_LDA(dst, b, h) do { _Pragma("unroll") for (int m = 0; m < 4; ++m) _Pragma("unroll") for (int k = 0; k < 2; ++k) dst[m][k] = *(const PG8_LAS bf16x8*)(lds + PG8_SA(b, h) + aoff + m * 2048 + k * 1024); } while (0)
; #define PG8_MMA(ai, bj, At, Bt) do { __builtin_amdgcn_s_setprio(1); _Pragma("unroll") for (int m = 0; m < 4; ++m) _Pragma("unroll") for (int n = 0; n < 2; ++n) _Pragma("unroll") for (int k = 0; k < 2; ++k) \
;         acc[ai][bj][m][n] = __builtin_amdgcn_mfma_f32_16x16x32_bf16(Bt[n][k], At[m][k], acc[ai][bj][m][n], 0, 0, 0); __builtin_amdgcn_s_setprio(0); } while (0)
; #define PG8_WAIT_V(n) asm volatile("s_waitcnt vmcnt(" #n ")" ::: "memory")
; #define PG8_WAIT_L(n) asm volatile("s_waitcnt lgkmcnt(" #n ")" ::: "memory")
; #define PG8_BAR __builtin_amdgcn_s_barrier()
; #define PG8_SCHED __builtin_amdgcn_sched_barrier(0)
; template <class Epi, class Sched, bool ALIGN_EPI = false, bool SP2 = false>
; __device__ __forceinline__ void gemm_phase(PG8_LAS unsigned char* lds, const Gemm g, const Sched& S, const Epi& E) {
;     ...
;             PG8_LDA(At, 1, 1); PG8_STAGE(PG8_SB(1, 0), b3, voffB); PG8_STAGE(PG8_SB(1, 1), b3 + hstep, voffB); PG8_STAGE(PG8_SA(1, 0), a3, voffA);
;             PG8_WAIT_V(8); PG8_WAIT_L(0); PG8_BAR; PG8_MMA(1, 0, At, B0); PG8_MMA(1, 1, At, B1); PG8_BAR; PG8_SCHED;
	s_add_i32 s22, s56, s25
	s_mov_b32 m0, s22
	ds_read_b128 v[216:219], v155 offset:49152
	ds_read_b128 v[220:223], v155 offset:50176
	ds_read_b128 v[224:227], v155 offset:51200
	ds_read_b128 v[228:231], v155 offset:52224
	ds_read_b128 v[232:235], v155 offset:53248
	ds_read_b128 v[236:239], v155 offset:54272
	ds_read_b128 v[240:243], v155 offset:55296
	ds_read_b128 v[244:247], v155 offset:56320
	s_add_u32 vcc_lo, s20, 0x80
	s_addc_u32 vcc_hi, s21, 0
	global_load_lds_dwordx4 v2, vcc
	s_add_i32 m0, s22, 0x2000
	s_add_u32 s20, s20, 0x80080
	s_addc_u32 s21, s21, 0
	s_add_i32 s22, s57, s25
	s_add_u32 vcc_lo, s20, 0xfff80000
	s_addc_u32 vcc_hi, s21, -1
	global_load_lds_dwordx4 v0, vcc
	s_mov_b32 m0, s22
	s_nop 0
	global_load_lds_dwordx4 v2, s[20:21]
	s_add_i32 m0, s22, 0x2000
	s_nop 0
	global_load_lds_dwordx4 v0, s[20:21]
	v_lshl_add_u64 v[150:151], v[250:251], 0, s[36:37]
	s_mov_b32 m0, s31
	s_nop 0
	global_load_lds_dwordx4 v[150:151], off
	v_lshl_add_u64 v[150:151], v[252:253], 0, s[36:37]
	s_mov_b32 m0, s34
	s_nop 0
	global_load_lds_dwordx4 v[150:151], off
	s_waitcnt vmcnt(8)
	s_waitcnt lgkmcnt(0)
	s_barrier
	s_setprio 1
	s_waitcnt lgkmcnt(0)
	v_mfma_f32_16x16x32_bf16 v[64:67], v[184:187], v[216:219], v[64:67]
	v_mfma_f32_16x16x32_bf16 v[56:59], v[192:195], v[216:219], v[56:59]
	v_mfma_f32_16x16x32_bf16 v[48:51], v[184:187], v[224:227], v[48:51]
	v_mfma_f32_16x16x32_bf16 v[40:43], v[192:195], v[224:227], v[40:43]
	v_mfma_f32_16x16x32_bf16 v[32:35], v[184:187], v[232:235], v[32:35]
	v_mfma_f32_16x16x32_bf16 v[24:27], v[192:195], v[232:235], v[24:27]
	v_mfma_f32_16x16x32_bf16 v[16:19], v[184:187], v[240:243], v[16:19]
	v_mfma_f32_16x16x32_bf16 v[8:11], v[192:195], v[240:243], v[8:11]
	v_mfma_f32_16x16x32_bf16 v[64:67], v[188:191], v[220:223], v[64:67]
	v_mfma_f32_16x16x32_bf16 v[56:59], v[196:199], v[220:223], v[56:59]
	v_mfma_f32_16x16x32_bf16 v[48:51], v[188:191], v[228:231], v[48:51]
	v_mfma_f32_16x16x32_bf16 v[40:43], v[196:199], v[228:231], v[40:43]
	v_mfma_f32_16x16x32_bf16 v[32:35], v[188:191], v[236:239], v[32:35]
	v_mfma_f32_16x16x32_bf16 v[24:27], v[196:199], v[236:239], v[24:27]
	v_mfma_f32_16x16x32_bf16 v[16:19], v[188:191], v[244:247], v[16:19]
	v_mfma_f32_16x16x32_bf16 v[8:11], v[196:199], v[244:247], v[8:11]
	s_setprio 0
	s_setprio 1
	v_mfma_f32_16x16x32_bf16 v[60:63], v[200:203], v[216:219], v[60:63]
	v_mfma_f32_16x16x32_bf16 v[52:55], v[208:211], v[216:219], v[52:55]
	v_mfma_f32_16x16x32_bf16 v[44:47], v[200:203], v[224:227], v[44:47]
	v_mfma_f32_16x16x32_bf16 v[36:39], v[208:211], v[224:227], v[36:39]
	v_mfma_f32_16x16x32_bf16 v[28:31], v[200:203], v[232:235], v[28:31]
	v_mfma_f32_16x16x32_bf16 v[20:23], v[208:211], v[232:235], v[20:23]
	v_mfma_f32_16x16x32_bf16 v[12:15], v[200:203], v[240:243], v[12:15]
	v_mfma_f32_16x16x32_bf16 v[4:7], v[208:211], v[240:243], v[4:7]
	v_mfma_f32_16x16x32_bf16 v[60:63], v[204:207], v[220:223], v[60:63]
	v_mfma_f32_16x16x32_bf16 v[52:55], v[212:215], v[220:223], v[52:55]
	v_mfma_f32_16x16x32_bf16 v[44:47], v[204:207], v[228:231], v[44:47]
	v_mfma_f32_16x16x32_bf16 v[36:39], v[212:215], v[228:231], v[36:39]
	v_mfma_f32_16x16x32_bf16 v[28:31], v[204:207], v[236:239], v[28:31]
	v_mfma_f32_16x16x32_bf16 v[20:23], v[212:215], v[236:239], v[20:23]
	v_mfma_f32_16x16x32_bf16 v[12:15], v[204:207], v[244:247], v[12:15]
	v_mfma_f32_16x16x32_bf16 v[4:7], v[212:215], v[244:247], v[4:7]
	s_setprio 0
	s_barrier
	s_add_i32 s51, s51, 2
	s_add_u32 s18, s18, 0x100
	s_addc_u32 s19, s19, 0
	s_add_u32 s45, s45, 0x100
	s_addc_u32 s50, s50, 0
	s_cmp_gt_u32 s51, 29

; #define PG8_STAGE(bufoff, gbase, voff) do { _Pragma("unroll") for (int _i = 0; _i < 2; ++_i) \
;         __builtin_amdgcn_global_load_lds((const unsigned*)((const char*)(gbase) + (voff)[_i]), (PG8_LAS unsigned*)(lds + (bufoff) + ldsw + _i * 8192), 16, 0, 0); } while (0)
; #define PG8_LDA(dst, b, h) do { _Pragma("unroll") for (int m = 0; m < 4; ++m) _Pragma("unroll") for (int k = 0; k < 2; ++k) dst[m][k] = *(const PG8_LAS bf16x8*)(lds + PG8_SA(b, h) + aoff + m * 2048 + k * 1024); } while (0)
; #define PG8_LDB(dst, b, h) do { _Pragma("unroll") for (int n = 0; n < 2; ++n) _Pragma("unroll") for (int k = 0; k < 2; ++k) dst[n][k] = *(const PG8_LAS bf16x8*)(lds + PG8_SB(b, h) + boff + n * 2048 + k * 1024); } while (0)
; #define PG8_MMA(ai, bj, At, Bt) do { __builtin_amdgcn_s_setprio(1); _Pragma("unroll") for (int m = 0; m < 4; ++m) _Pragma("unroll") for (int n = 0; n < 2; ++n) _Pragma("unroll") for (int k = 0; k < 2; ++k) \
;         acc[ai][bj][m][n] = __builtin_amdgcn_mfma_f32_16x16x32_bf16(Bt[n][k], At[m][k], acc[ai][bj][m][n], 0, 0, 0); __builtin_amdgcn_s_setprio(0); } while (0)
; #define PG8_WAIT_V(n) asm volatile("s_waitcnt vmcnt(" #n ")" ::: "memory")
; #define PG8_BAR __builtin_amdgcn_s_barrier()
; template <class Epi, class Sched, bool ALIGN_EPI = false, bool SP2 = false>
; __device__ __forceinline__ void gemm_phase(PG8_LAS unsigned char* lds, const Gemm g, const Sched& S, const Epi& E) {
;     ...
;         for (int t = 0; t < nt; t += 2) {
;             const bool last = (t == nt - 2);
;             const char* a1 = cA + (size_t)(t + 1) * kstep;
;             const char* a2 = last ? nA : cA + (size_t)(t + 2) * kstep; const char* b2 = last ? nB : cB + (size_t)(t + 2) * kstep;
;             const char* a3 = a2 + kstep; const char* b3 = b2 + kstep;
;             if (last && has_next) S.a_ready(nxt);
;             if constexpr (SP2) {
;             PG8_LDB(B0, 0, 0); PG8_LDB(B1, 0, 1); PG8_SCHED; PG8_LDA(At, 0, 0); PG8_STAGE(PG8_SA(1, 1), a1 + hstep, voffA);
;             PG8_WAIT_V(8); PG8_WAIT_L(0); PG8_BAR; PG8_MMA(0, 0, At, B0); PG8_MMA(0, 1, At, B1); PG8_BAR; PG8_SCHED;
;             PG8_LDA(At, 0, 1); PG8_STAGE(PG8_SB(0, 0), b2, voffB); PG8_STAGE(PG8_SB(0, 1), b2 + hstep, voffB); PG8_STAGE(PG8_SA(0, 0), a2, voffA);
;             PG8_WAIT_V(8); PG8_WAIT_L(0); PG8_BAR; PG8_MMA(1, 0, At, B0); PG8_MMA(1, 1, At, B1); PG8_BAR; PG8_SCHED;
.LBB0_166:
	s_add_u32 s51, s16, 0x100
	s_addc_u32 s56, s17, 0
	s_mov_b32 s57, -2
	s_waitcnt lgkmcnt(0)
	s_add_u32 s16, s14, 0x100
	s_addc_u32 s17, s15, 0
	s_add_i32 s63, 0, 0x10000
	s_cmpk_eq_i32 s57, 0x54
	s_cselect_b32 s21, s7, s17
	s_cselect_b32 s20, s6, s16
	s_cselect_b32 s19, s13, s56
	s_cselect_b32 s18, s12, s51
	s_add_i32 s64, 0, 0x14000
	v_add_u32_e32 v162, s63, v185
	v_add_u32_e32 v166, s64, v185
	ds_read_b128 v[132:135], v162
	ds_read_b128 v[136:139], v162 offset:1024
	ds_read_b128 v[158:161], v162 offset:2048
	ds_read_b128 v[162:165], v162 offset:3072
	ds_read_b128 v[188:191], v166
	ds_read_b128 v[192:195], v166 offset:1024
	ds_read_b128 v[196:199], v166 offset:2048
	ds_read_b128 v[200:203], v166 offset:3072
	s_add_i32 m0, s26, 0xc000
	ds_read_b128 v[204:207], v187
	ds_read_b128 v[208:211], v187 offset:1024
	ds_read_b128 v[212:215], v187 offset:2048
	ds_read_b128 v[216:219], v187 offset:3072
	ds_read_b128 v[220:223], v187 offset:4096
	ds_read_b128 v[224:227], v187 offset:5120
	ds_read_b128 v[228:231], v187 offset:6144
	ds_read_b128 v[232:235], v187 offset:7168
	global_load_lds_dwordx4 v154, s[14:15]
	s_add_i32 m0, s26, 0xe000
	s_nop 0
	global_load_lds_dwordx4 v156, s[14:15]
	s_waitcnt vmcnt(8)
	s_waitcnt lgkmcnt(0)
	s_barrier
	s_setprio 1
	s_waitcnt lgkmcnt(0)
	v_mfma_f32_16x16x32_bf16 v[128:131], v[132:135], v[204:207], 0
	v_mfma_f32_16x16x32_bf16 v[124:127], v[158:161], v[204:207], 0
	v_mfma_f32_16x16x32_bf16 v[112:115], v[132:135], v[212:215], 0
	v_mfma_f32_16x16x32_bf16 v[108:111], v[158:161], v[212:215], 0
	v_mfma_f32_16x16x32_bf16 v[96:99], v[132:135], v[220:223], 0
	v_mfma_f32_16x16x32_bf16 v[92:95], v[158:161], v[220:223], 0
	v_mfma_f32_16x16x32_bf16 v[80:83], v[132:135], v[228:231], 0
	v_mfma_f32_16x16x32_bf16 v[76:79], v[158:161], v[228:231], 0
	v_mfma_f32_16x16x32_bf16 v[128:131], v[136:139], v[208:211], v[128:131]
	v_mfma_f32_16x16x32_bf16 v[124:127], v[162:165], v[208:211], v[124:127]
	v_mfma_f32_16x16x32_bf16 v[112:115], v[136:139], v[216:219], v[112:115]
	v_mfma_f32_16x16x32_bf16 v[108:111], v[162:165], v[216:219], v[108:111]
	v_mfma_f32_16x16x32_bf16 v[96:99], v[136:139], v[224:227], v[96:99]
	v_mfma_f32_16x16x32_bf16 v[92:95], v[162:165], v[224:227], v[92:95]
	v_mfma_f32_16x16x32_bf16 v[80:83], v[136:139], v[232:235], v[80:83]
	v_mfma_f32_16x16x32_bf16 v[76:79], v[162:165], v[232:235], v[76:79]
	s_setprio 0
	s_setprio 1
	v_mfma_f32_16x16x32_bf16 v[120:123], v[188:191], v[204:207], 0
	v_mfma_f32_16x16x32_bf16 v[116:119], v[196:199], v[204:207], 0
	v_mfma_f32_16x16x32_bf16 v[104:107], v[188:191], v[212:215], 0
	v_mfma_f32_16x16x32_bf16 v[100:103], v[196:199], v[212:215], 0
	v_mfma_f32_16x16x32_bf16 v[88:91], v[188:191], v[220:223], 0
	v_mfma_f32_16x16x32_bf16 v[84:87], v[196:199], v[220:223], 0
	v_mfma_f32_16x16x32_bf16 v[72:75], v[188:191], v[228:231], 0
	v_mfma_f32_16x16x32_bf16 v[68:71], v[196:199], v[228:231], 0
	v_mfma_f32_16x16x32_bf16 v[120:123], v[192:195], v[208:211], v[120:123]
	v_mfma_f32_16x16x32_bf16 v[116:119], v[200:203], v[208:211], v[116:119]
	v_mfma_f32_16x16x32_bf16 v[104:107], v[192:195], v[216:219], v[104:107]
	v_mfma_f32_16x16x32_bf16 v[100:103], v[200:203], v[216:219], v[100:103]
	v_mfma_f32_16x16x32_bf16 v[88:91], v[192:195], v[224:227], v[88:91]
	v_mfma_f32_16x16x32_bf16 v[84:87], v[200:203], v[224:227], v[84:87]
	v_mfma_f32_16x16x32_bf16 v[72:75], v[192:195], v[232:235], v[72:75]
	v_mfma_f32_16x16x32_bf16 v[68:71], v[200:203], v[232:235], v[68:71]
	s_setprio 0
	s_barrier
	s_add_i32 s14, s63, s25
	s_mov_b32 m0, s14
	ds_read_b128 v[204:207], v187 offset:16384
	ds_read_b128 v[208:211], v187 offset:17408
	ds_read_b128 v[212:215], v187 offset:18432
	ds_read_b128 v[216:219], v187 offset:19456
	ds_read_b128 v[220:223], v187 offset:20480
	ds_read_b128 v[224:227], v187 offset:21504
	ds_read_b128 v[228:231], v187 offset:22528
	ds_read_b128 v[232:235], v187 offset:23552
	global_load_lds_dwordx4 v2, s[18:19]
	s_add_i32 m0, s14, 0x2000
	s_add_u32 s14, s18, 0x160000
	v_lshl_add_u64 v[236:237], s[18:19], 0, v[152:153]
	s_addc_u32 s15, s19, 0
	s_add_i32 s63, s64, s25
	global_load_lds_dwordx4 v[236:237], off
	s_mov_b32 m0, s63
	global_load_lds_dwordx4 v2, s[14:15]
	s_add_i32 m0, s63, 0x2000
	s_nop 0
	global_load_lds_dwordx4 v152, s[14:15]
	s_mov_b32 m0, s26
	s_nop 0
	global_load_lds_dwordx4 v0, s[20:21]
	s_mov_b32 m0, s27
	s_nop 0
	global_load_lds_dwordx4 v150, s[20:21]
	s_waitcnt vmcnt(8)
	s_waitcnt lgkmcnt(0)
	s_barrier
	s_setprio 1
	s_waitcnt lgkmcnt(0)
	v_mfma_f32_16x16x32_bf16 v[64:67], v[132:135], v[204:207], 0
	v_mfma_f32_16x16x32_bf16 v[60:63], v[158:161], v[204:207], 0
	v_mfma_f32_16x16x32_bf16 v[48:51], v[132:135], v[212:215], 0
	v_mfma_f32_16x16x32_bf16 v[44:47], v[158:161], v[212:215], 0
	v_mfma_f32_16x16x32_bf16 v[32:35], v[132:135], v[220:223], 0
	v_mfma_f32_16x16x32_bf16 v[28:31], v[158:161], v[220:223], 0
	v_mfma_f32_16x16x32_bf16 v[16:19], v[132:135], v[228:231], 0
	v_mfma_f32_16x16x32_bf16 v[12:15], v[158:161], v[228:231], 0
	v_mfma_f32_16x16x32_bf16 v[64:67], v[136:139], v[208:211], v[64:67]
	v_mfma_f32_16x16x32_bf16 v[60:63], v[162:165], v[208:211], v[60:63]
	v_mfma_f32_16x16x32_bf16 v[48:51], v[136:139], v[216:219], v[48:51]
	v_mfma_f32_16x16x32_bf16 v[44:47], v[162:165], v[216:219], v[44:47]
	v_mfma_f32_16x16x32_bf16 v[32:35], v[136:139], v[224:227], v[32:35]
	v_mfma_f32_16x16x32_bf16 v[28:31], v[162:165], v[224:227], v[28:31]
	v_mfma_f32_16x16x32_bf16 v[16:19], v[136:139], v[232:235], v[16:19]
	v_mfma_f32_16x16x32_bf16 v[12:15], v[162:165], v[232:235], v[12:15]
	s_setprio 0
	s_setprio 1
	v_mfma_f32_16x16x32_bf16 v[56:59], v[188:191], v[204:207], 0
	v_mfma_f32_16x16x32_bf16 v[52:55], v[196:199], v[204:207], 0
	v_mfma_f32_16x16x32_bf16 v[40:43], v[188:191], v[212:215], 0
	v_mfma_f32_16x16x32_bf16 v[36:39], v[196:199], v[212:215], 0
	v_mfma_f32_16x16x32_bf16 v[24:27], v[188:191], v[220:223], 0
	v_mfma_f32_16x16x32_bf16 v[20:23], v[196:199], v[220:223], 0
	v_mfma_f32_16x16x32_bf16 v[8:11], v[188:191], v[228:231], 0
	v_mfma_f32_16x16x32_bf16 v[4:7], v[196:199], v[228:231], 0
	v_mfma_f32_16x16x32_bf16 v[56:59], v[192:195], v[208:211], v[56:59]
	v_mfma_f32_16x16x32_bf16 v[52:55], v[200:203], v[208:211], v[52:55]
	v_mfma_f32_16x16x32_bf16 v[40:43], v[192:195], v[216:219], v[40:43]
	v_mfma_f32_16x16x32_bf16 v[36:39], v[200:203], v[216:219], v[36:39]
	v_mfma_f32_16x16x32_bf16 v[24:27], v[192:195], v[224:227], v[24:27]
	v_mfma_f32_16x16x32_bf16 v[20:23], v[200:203], v[224:227], v[20:23]
	v_mfma_f32_16x16x32_bf16 v[8:11], v[192:195], v[232:235], v[8:11]
	v_mfma_f32_16x16x32_bf16 v[4:7], v[200:203], v[232:235], v[4:7]
	s_setprio 0
	s_barrier
; #define PG8_STAGE(bufoff, gbase, voff) do { _Pragma("unroll") for (int _i = 0; _i < 2; ++_i) \
;         __builtin_amdgcn_global_load_lds((const unsigned*)((const char*)(gbase) + (voff)[_i]), (PG8_LAS unsigned*)(lds + (bufoff) + ldsw + _i * 8192), 16, 0, 0); } while (0)
; #define PG8_LDA(dst, b, h) do { _Pragma("unroll") for (int m = 0; m < 4; ++m) _Pragma("unroll") for (int k = 0; k < 2; ++k) dst[m][k] = *(const PG8_LAS bf16x8*)(lds + PG8_SA(b, h) + aoff + m * 2048 + k * 1024); } while (0)
; #define PG8_LDB(dst, b, h) do { _Pragma("unroll") for (int n = 0; n < 2; ++n) _Pragma("unroll") for (int k = 0; k < 2; ++k) dst[n][k] = *(const PG8_LAS bf16x8*)(lds + PG8_SB(b, h) + boff + n * 2048 + k * 1024); } while (0)
; #define PG8_MMA(ai, bj, At, Bt) do { __builtin_amdgcn_s_setprio(1); _Pragma("unroll") for (int m = 0; m < 4; ++m) _Pragma("unroll") for (int n = 0; n < 2; ++n) _Pragma("unroll") for (int k = 0; k < 2; ++k) \
;         acc[ai][bj][m][n] = __builtin_amdgcn_mfma_f32_16x16x32_bf16(Bt[n][k], At[m][k], acc[ai][bj][m][n], 0, 0, 0); __builtin_amdgcn_s_setprio(0); } while (0)
; #define PG8_WAIT_V(n) asm volatile("s_waitcnt vmcnt(" #n ")" ::: "memory")
; #define PG8_WAIT_L(n) asm volatile("s_waitcnt lgkmcnt(" #n ")" ::: "memory")
; #define PG8_BAR __builtin_amdgcn_s_barrier()
; #define PG8_SCHED __builtin_amdgcn_sched_barrier(0)
; template <class Epi, class Sched, bool ALIGN_EPI = false, bool SP2 = false>
; __device__ __forceinline__ void gemm_phase(PG8_LAS unsigned char* lds, const Gemm g, const Sched& S, const Epi& E) {
;     ...
;             PG8_LDB(B0, 1, 0); PG8_LDB(B1, 1, 1); PG8_SCHED; PG8_LDA(At, 1, 0); PG8_STAGE(PG8_SA(0, 1), a2 + hstep, voffA);
;             PG8_WAIT_V(8); PG8_WAIT_L(0); PG8_BAR; PG8_MMA(0, 0, At, B0); PG8_MMA(0, 1, At, B1); PG8_BAR; PG8_SCHED;
;             PG8_LDA(At, 1, 1); PG8_STAGE(PG8_SB(1, 0), b3, voffB); PG8_STAGE(PG8_SB(1, 1), b3 + hstep, voffB); PG8_STAGE(PG8_SA(1, 0), a3, voffA);
;             PG8_WAIT_V(8); PG8_WAIT_L(0); PG8_BAR; PG8_MMA(1, 0, At, B0); PG8_MMA(1, 1, At, B1); PG8_BAR; PG8_SCHED;
	s_add_i32 s63, 0, 0x18000
	s_add_i32 s64, 0, 0x1c000
	v_add_u32_e32 v162, s63, v185
	v_add_u32_e32 v200, s64, v185
	ds_read_b128 v[132:135], v162
	ds_read_b128 v[136:139], v162 offset:1024
	ds_read_b128 v[158:161], v162 offset:2048
	ds_read_b128 v[162:165], v162 offset:3072
	ds_read_b128 v[188:191], v200
	ds_read_b128 v[192:195], v200 offset:1024
	ds_read_b128 v[196:199], v200 offset:2048
	ds_read_b128 v[200:203], v200 offset:3072
	s_add_u32 s14, s20, 0x160000
	s_addc_u32 s15, s21, 0
	s_mov_b32 m0, s28
	ds_read_b128 v[204:207], v187 offset:32768
	ds_read_b128 v[208:211], v187 offset:33792
	ds_read_b128 v[212:215], v187 offset:34816
	ds_read_b128 v[216:219], v187 offset:35840
	ds_read_b128 v[220:223], v187 offset:36864
	ds_read_b128 v[224:227], v187 offset:37888
	ds_read_b128 v[228:231], v187 offset:38912
	ds_read_b128 v[232:235], v187 offset:39936
	global_load_lds_dwordx4 v0, s[14:15]
	s_mov_b32 m0, s29
	s_nop 0
	global_load_lds_dwordx4 v150, s[14:15]
	s_waitcnt vmcnt(8)
	s_waitcnt lgkmcnt(0)
	s_barrier
	s_setprio 1
	s_waitcnt lgkmcnt(0)
	v_mfma_f32_16x16x32_bf16 v[128:131], v[132:135], v[204:207], v[128:131]
	v_mfma_f32_16x16x32_bf16 v[124:127], v[158:161], v[204:207], v[124:127]
	v_mfma_f32_16x16x32_bf16 v[112:115], v[132:135], v[212:215], v[112:115]
	v_mfma_f32_16x16x32_bf16 v[108:111], v[158:161], v[212:215], v[108:111]
	v_mfma_f32_16x16x32_bf16 v[96:99], v[132:135], v[220:223], v[96:99]
	v_mfma_f32_16x16x32_bf16 v[92:95], v[158:161], v[220:223], v[92:95]
	v_mfma_f32_16x16x32_bf16 v[80:83], v[132:135], v[228:231], v[80:83]
	v_mfma_f32_16x16x32_bf16 v[76:79], v[158:161], v[228:231], v[76:79]
	v_mfma_f32_16x16x32_bf16 v[128:131], v[136:139], v[208:211], v[128:131]
	v_mfma_f32_16x16x32_bf16 v[124:127], v[162:165], v[208:211], v[124:127]
	v_mfma_f32_16x16x32_bf16 v[112:115], v[136:139], v[216:219], v[112:115]
	v_mfma_f32_16x16x32_bf16 v[108:111], v[162:165], v[216:219], v[108:111]
	v_mfma_f32_16x16x32_bf16 v[96:99], v[136:139], v[224:227], v[96:99]
	v_mfma_f32_16x16x32_bf16 v[92:95], v[162:165], v[224:227], v[92:95]
	v_mfma_f32_16x16x32_bf16 v[80:83], v[136:139], v[232:235], v[80:83]
	v_mfma_f32_16x16x32_bf16 v[76:79], v[162:165], v[232:235], v[76:79]
	s_setprio 0
	s_setprio 1
	v_mfma_f32_16x16x32_bf16 v[120:123], v[188:191], v[204:207], v[120:123]
	v_mfma_f32_16x16x32_bf16 v[116:119], v[196:199], v[204:207], v[116:119]
	v_mfma_f32_16x16x32_bf16 v[104:107], v[188:191], v[212:215], v[104:107]
	v_mfma_f32_16x16x32_bf16 v[100:103], v[196:199], v[212:215], v[100:103]
	v_mfma_f32_16x16x32_bf16 v[88:91], v[188:191], v[220:223], v[88:91]
	v_mfma_f32_16x16x32_bf16 v[84:87], v[196:199], v[220:223], v[84:87]
	v_mfma_f32_16x16x32_bf16 v[72:75], v[188:191], v[228:231], v[72:75]
	v_mfma_f32_16x16x32_bf16 v[68:71], v[196:199], v[228:231], v[68:71]
	v_mfma_f32_16x16x32_bf16 v[120:123], v[192:195], v[208:211], v[120:123]
	v_mfma_f32_16x16x32_bf16 v[116:119], v[200:203], v[208:211], v[116:119]
	v_mfma_f32_16x16x32_bf16 v[104:107], v[192:195], v[216:219], v[104:107]
	v_mfma_f32_16x16x32_bf16 v[100:103], v[200:203], v[216:219], v[100:103]
	v_mfma_f32_16x16x32_bf16 v[88:91], v[192:195], v[224:227], v[88:91]
	v_mfma_f32_16x16x32_bf16 v[84:87], v[200:203], v[224:227], v[84:87]
	v_mfma_f32_16x16x32_bf16 v[72:75], v[192:195], v[232:235], v[72:75]
	v_mfma_f32_16x16x32_bf16 v[68:71], v[200:203], v[232:235], v[68:71]
	s_setprio 0
	s_barrier
	s_add_i32 s14, s63, s25
	s_mov_b32 m0, s14
	ds_read_b128 v[204:207], v187 offset:49152
	ds_read_b128 v[208:211], v187 offset:50176
	ds_read_b128 v[212:215], v187 offset:51200
	ds_read_b128 v[216:219], v187 offset:52224
	ds_read_b128 v[220:223], v187 offset:53248
	ds_read_b128 v[224:227], v187 offset:54272
	ds_read_b128 v[228:231], v187 offset:55296
	ds_read_b128 v[232:235], v187 offset:56320
	s_add_u32 vcc_lo, s18, 0x80
	s_addc_u32 vcc_hi, s19, 0
	global_load_lds_dwordx4 v2, vcc
	s_add_i32 m0, s14, 0x2000
	s_add_u32 s14, s18, 0x160080
	v_lshl_add_u64 v[166:167], v[236:237], 0, s[36:37]
	s_addc_u32 s15, s19, 0
	s_add_i32 s18, s64, s25
	global_load_lds_dwordx4 v[166:167], off
	s_mov_b32 m0, s18
	s_nop 0
	global_load_lds_dwordx4 v2, s[14:15]
	v_lshl_add_u64 v[166:167], s[14:15], 0, v[152:153]
	s_add_i32 m0, s18, 0x2000
	s_nop 0
	global_load_lds_dwordx4 v[166:167], off
	s_mov_b32 m0, s30
	s_nop 0
	s_add_u32 vcc_lo, s20, 0x80
	s_addc_u32 vcc_hi, s21, 0
	global_load_lds_dwordx4 v0, vcc
	s_mov_b32 m0, s31
	s_nop 0
	s_add_u32 vcc_lo, s20, 0x80
	s_addc_u32 vcc_hi, s21, 0
	global_load_lds_dwordx4 v150, vcc
	s_waitcnt vmcnt(8)
	s_waitcnt lgkmcnt(0)
	s_barrier
	s_setprio 1
	s_waitcnt lgkmcnt(0)
	v_mfma_f32_16x16x32_bf16 v[64:67], v[132:135], v[204:207], v[64:67]
	v_mfma_f32_16x16x32_bf16 v[60:63], v[158:161], v[204:207], v[60:63]
	v_mfma_f32_16x16x32_bf16 v[48:51], v[132:135], v[212:215], v[48:51]
	v_mfma_f32_16x16x32_bf16 v[44:47], v[158:161], v[212:215], v[44:47]
	v_mfma_f32_16x16x32_bf16 v[32:35], v[132:135], v[220:223], v[32:35]
	v_mfma_f32_16x16x32_bf16 v[28:31], v[158:161], v[220:223], v[28:31]
	v_mfma_f32_16x16x32_bf16 v[16:19], v[132:135], v[228:231], v[16:19]
	v_mfma_f32_16x16x32_bf16 v[12:15], v[158:161], v[228:231], v[12:15]
	v_mfma_f32_16x16x32_bf16 v[64:67], v[136:139], v[208:211], v[64:67]
	v_mfma_f32_16x16x32_bf16 v[60:63], v[162:165], v[208:211], v[60:63]
	v_mfma_f32_16x16x32_bf16 v[48:51], v[136:139], v[216:219], v[48:51]
	v_mfma_f32_16x16x32_bf16 v[44:47], v[162:165], v[216:219], v[44:47]
	v_mfma_f32_16x16x32_bf16 v[32:35], v[136:139], v[224:227], v[32:35]
	v_mfma_f32_16x16x32_bf16 v[28:31], v[162:165], v[224:227], v[28:31]
	v_mfma_f32_16x16x32_bf16 v[16:19], v[136:139], v[232:235], v[16:19]
	v_mfma_f32_16x16x32_bf16 v[12:15], v[162:165], v[232:235], v[12:15]
	s_setprio 0
	s_setprio 1
	v_mfma_f32_16x16x32_bf16 v[56:59], v[188:191], v[204:207], v[56:59]
	v_mfma_f32_16x16x32_bf16 v[52:55], v[196:199], v[204:207], v[52:55]
	v_mfma_f32_16x16x32_bf16 v[40:43], v[188:191], v[212:215], v[40:43]
	v_mfma_f32_16x16x32_bf16 v[36:39], v[196:199], v[212:215], v[36:39]
	v_mfma_f32_16x16x32_bf16 v[24:27], v[188:191], v[220:223], v[24:27]
	v_mfma_f32_16x16x32_bf16 v[20:23], v[196:199], v[220:223], v[20:23]
	v_mfma_f32_16x16x32_bf16 v[8:11], v[188:191], v[228:231], v[8:11]
	v_mfma_f32_16x16x32_bf16 v[4:7], v[196:199], v[228:231], v[4:7]
	v_mfma_f32_16x16x32_bf16 v[56:59], v[192:195], v[208:211], v[56:59]
	v_mfma_f32_16x16x32_bf16 v[52:55], v[200:203], v[208:211], v[52:55]
	v_mfma_f32_16x16x32_bf16 v[40:43], v[192:195], v[216:219], v[40:43]
	v_mfma_f32_16x16x32_bf16 v[36:39], v[200:203], v[216:219], v[36:39]
	v_mfma_f32_16x16x32_bf16 v[24:27], v[192:195], v[224:227], v[24:27]
	v_mfma_f32_16x16x32_bf16 v[20:23], v[200:203], v[224:227], v[20:23]
	v_mfma_f32_16x16x32_bf16 v[8:11], v[192:195], v[232:235], v[8:11]
	v_mfma_f32_16x16x32_bf16 v[4:7], v[200:203], v[232:235], v[4:7]
	s_setprio 0
	s_barrier
	s_add_i32 s57, s57, 2
	s_add_u32 s51, s51, 0x100
	s_addc_u32 s56, s56, 0
	s_cmpk_gt_u32 s57, 0x55
	s_mov_b64 s[14:15], s[16:17]

; #define PG8_STAGE(bufoff, gbase, voff) do { _Pragma("unroll") for (int _i = 0; _i < 2; ++_i) \
;         __builtin_amdgcn_global_load_lds((const unsigned*)((const char*)(gbase) + (voff)[_i]), (PG8_LAS unsigned*)(lds + (bufoff) + ldsw + _i * 8192), 16, 0, 0); } while (0)
; #define PG8_LDA(dst, b, h) do { _Pragma("unroll") for (int m = 0; m < 4; ++m) _Pragma("unroll") for (int k = 0; k < 2; ++k) dst[m][k] = *(const PG8_LAS bf16x8*)(lds + PG8_SA(b, h) + aoff + m * 2048 + k * 1024); } while (0)
; #define PG8_LDB(dst, b, h) do { _Pragma("unroll") for (int n = 0; n < 2; ++n) _Pragma("unroll") for (int k = 0; k < 2; ++k) dst[n][k] = *(const PG8_LAS bf16x8*)(lds + PG8_SB(b, h) + boff + n * 2048 + k * 1024); } while (0)
; #define PG8_MMA(ai, bj, At, Bt) do { __builtin_amdgcn_s_setprio(1); _Pragma("unroll") for (int m = 0; m < 4; ++m) _Pragma("unroll") for (int n = 0; n < 2; ++n) _Pragma("unroll") for (int k = 0; k < 2; ++k) \
;         acc[ai][bj][m][n] = __builtin_amdgcn_mfma_f32_16x16x32_bf16(Bt[n][k], At[m][k], acc[ai][bj][m][n], 0, 0, 0); __builtin_amdgcn_s_setprio(0); } while (0)
; #define PG8_WAIT_V(n) asm volatile("s_waitcnt vmcnt(" #n ")" ::: "memory")
; template <class Epi, class Sched, bool ALIGN_EPI = false, bool SP2 = false>
; __device__ __forceinline__ void gemm_phase(PG8_LAS unsigned char* lds, const Gemm g, const Sched& S, const Epi& E) {
;     ...
;         const char* nA = has_next ? (const char*)g.A + (size_t)nxt.pm * tstep : cA; const char* nB = has_next ? (const char*)g.Bt + (size_t)nxt.pn * tstep : cB;
;         for (int t = 0; t < nt; t += 2) {
;             const bool last = (t == nt - 2);
;             const char* a1 = cA + (size_t)(t + 1) * kstep;
;             const char* a2 = last ? nA : cA + (size_t)(t + 2) * kstep; const char* b2 = last ? nB : cB + (size_t)(t + 2) * kstep;
;             const char* a3 = a2 + kstep; const char* b3 = b2 + kstep;
;             if (last && has_next) S.a_ready(nxt);
;             if constexpr (SP2) {
;             PG8_LDB(B0, 0, 0); PG8_LDB(B1, 0, 1); PG8_SCHED; PG8_LDA(At, 0, 0); PG8_STAGE(PG8_SA(1, 1), a1 + hstep, voffA);
;             PG8_WAIT_V(8); PG8_WAIT_L(0); PG8_BAR; PG8_MMA(0, 0, At, B0); PG8_MMA(0, 1, At, B1); PG8_BAR; PG8_SCHED;
;             PG8_LDA(At, 0, 1); PG8_STAGE(PG8_SB(0, 0), b2, voffB); PG8_STAGE(PG8_SB(0, 1), b2 + hstep, voffB); PG8_STAGE(PG8_SA(0, 0), a2, voffA);
.LBB0_250:
	s_ashr_i32 s11, s10, 31
	s_lshl_b64 s[12:13], s[10:11], 20
	s_add_u32 s12, s46, s12
	s_addc_u32 s13, s47, s13
	s_and_b64 s[14:15], s[2:3], exec
	s_cselect_b32 s11, s13, s19
	s_cselect_b32 s45, s12, s18
	s_ashr_i32 s7, s6, 31
	s_lshl_b64 s[14:15], s[6:7], 20
	s_add_u32 s14, s25, s14
	s_addc_u32 s15, s26, s15
	s_and_b64 s[22:23], s[2:3], exec
	s_cselect_b32 s7, s15, s21
	s_cselect_b32 s50, s14, s20
	s_add_u32 s18, s18, 0x80080
	s_addc_u32 s19, s19, 0
	s_add_u32 s51, s20, 0x100
	s_addc_u32 s56, s21, 0
	s_mov_b32 s57, -2
	s_add_u32 s20, s18, 0xfff80080
	s_addc_u32 s21, s19, -1
	s_add_i32 s63, 0, 0x10000
	s_cmp_eq_u32 s57, 28
	s_cselect_b32 s23, s11, s21
	s_cselect_b32 s22, s45, s20
	v_add_u32_e32 v151, s63, v156
	s_cselect_b32 s21, s7, s56
	s_cselect_b32 s20, s50, s51
	s_add_i32 s66, 0, 0x14000
	ds_read_b128 v[184:187], v151
	ds_read_b128 v[188:191], v151 offset:1024
	ds_read_b128 v[192:195], v151 offset:2048
	ds_read_b128 v[196:199], v151 offset:3072
	v_add_u32_e32 v151, s66, v156
	ds_read_b128 v[200:203], v151
	ds_read_b128 v[204:207], v151 offset:1024
	ds_read_b128 v[208:211], v151 offset:2048
	ds_read_b128 v[212:215], v151 offset:3072
	s_add_i32 m0, s17, 0xc000
	ds_read_b128 v[216:219], v160
	ds_read_b128 v[220:223], v160 offset:1024
	ds_read_b128 v[224:227], v160 offset:2048
	ds_read_b128 v[228:231], v160 offset:3072
	ds_read_b128 v[232:235], v160 offset:4096
	ds_read_b128 v[236:239], v160 offset:5120
	ds_read_b128 v[240:243], v160 offset:6144
	ds_read_b128 v[244:247], v160 offset:7168
	global_load_lds_dwordx4 v136, s[18:19]
	s_add_i32 m0, s17, 0xe000
	s_nop 0
	global_load_lds_dwordx4 v138, s[18:19]
	s_waitcnt vmcnt(8)
	s_waitcnt lgkmcnt(0)
	s_barrier
	s_setprio 1
	s_waitcnt lgkmcnt(0)
	v_mfma_f32_16x16x32_bf16 v[128:131], v[184:187], v[216:219], 0
	v_mfma_f32_16x16x32_bf16 v[124:127], v[192:195], v[216:219], 0
	v_mfma_f32_16x16x32_bf16 v[112:115], v[184:187], v[224:227], 0
	v_mfma_f32_16x16x32_bf16 v[108:111], v[192:195], v[224:227], 0
	v_mfma_f32_16x16x32_bf16 v[96:99], v[184:187], v[232:235], 0
	v_mfma_f32_16x16x32_bf16 v[92:95], v[192:195], v[232:235], 0
	v_mfma_f32_16x16x32_bf16 v[80:83], v[184:187], v[240:243], 0
	v_mfma_f32_16x16x32_bf16 v[76:79], v[192:195], v[240:243], 0
	v_mfma_f32_16x16x32_bf16 v[128:131], v[188:191], v[220:223], v[128:131]
	v_mfma_f32_16x16x32_bf16 v[124:127], v[196:199], v[220:223], v[124:127]
	v_mfma_f32_16x16x32_bf16 v[112:115], v[188:191], v[228:231], v[112:115]
	v_mfma_f32_16x16x32_bf16 v[108:111], v[196:199], v[228:231], v[108:111]
	v_mfma_f32_16x16x32_bf16 v[96:99], v[188:191], v[236:239], v[96:99]
	v_mfma_f32_16x16x32_bf16 v[92:95], v[196:199], v[236:239], v[92:95]
	v_mfma_f32_16x16x32_bf16 v[80:83], v[188:191], v[244:247], v[80:83]
	v_mfma_f32_16x16x32_bf16 v[76:79], v[196:199], v[244:247], v[76:79]
	s_setprio 0
	s_setprio 1
	v_mfma_f32_16x16x32_bf16 v[120:123], v[200:203], v[216:219], 0
	v_mfma_f32_16x16x32_bf16 v[116:119], v[208:211], v[216:219], 0
	v_mfma_f32_16x16x32_bf16 v[104:107], v[200:203], v[224:227], 0
	v_mfma_f32_16x16x32_bf16 v[100:103], v[208:211], v[224:227], 0
	v_mfma_f32_16x16x32_bf16 v[88:91], v[200:203], v[232:235], 0
	v_mfma_f32_16x16x32_bf16 v[84:87], v[208:211], v[232:235], 0
	v_mfma_f32_16x16x32_bf16 v[72:75], v[200:203], v[240:243], 0
	v_mfma_f32_16x16x32_bf16 v[68:71], v[208:211], v[240:243], 0
	v_mfma_f32_16x16x32_bf16 v[120:123], v[204:207], v[220:223], v[120:123]
	v_mfma_f32_16x16x32_bf16 v[116:119], v[212:215], v[220:223], v[116:119]
	v_mfma_f32_16x16x32_bf16 v[104:107], v[204:207], v[228:231], v[104:107]
	v_mfma_f32_16x16x32_bf16 v[100:103], v[212:215], v[228:231], v[100:103]
	v_mfma_f32_16x16x32_bf16 v[88:91], v[204:207], v[236:239], v[88:91]
	v_mfma_f32_16x16x32_bf16 v[84:87], v[212:215], v[236:239], v[84:87]
	v_mfma_f32_16x16x32_bf16 v[72:75], v[204:207], v[244:247], v[72:75]
	v_mfma_f32_16x16x32_bf16 v[68:71], v[212:215], v[244:247], v[68:71]
	s_setprio 0
	s_barrier
	s_add_i32 s63, s63, s27
	s_mov_b32 m0, s63
	ds_read_b128 v[216:219], v160 offset:16384
	ds_read_b128 v[220:223], v160 offset:17408
	ds_read_b128 v[224:227], v160 offset:18432
	ds_read_b128 v[228:231], v160 offset:19456
	ds_read_b128 v[232:235], v160 offset:20480
	ds_read_b128 v[236:239], v160 offset:21504
	ds_read_b128 v[240:243], v160 offset:22528
	ds_read_b128 v[244:247], v160 offset:23552
	global_load_lds_dwordx4 v2, s[20:21]
	s_add_i32 m0, s63, 0x2000
	s_add_u32 s64, s20, 0x80000
	s_addc_u32 s65, s21, 0
	s_add_i32 s63, s66, s27
	global_load_lds_dwordx4 v0, s[20:21]
	s_mov_b32 m0, s63
	v_lshl_add_u64 v[250:251], s[22:23], 0, v[132:133]
	global_load_lds_dwordx4 v2, s[64:65]
	s_add_i32 m0, s63, 0x2000
	s_nop 0
	global_load_lds_dwordx4 v0, s[64:65]
	v_lshl_add_u64 v[248:249], s[22:23], 0, v[134:135]
	s_mov_b32 m0, s17
	s_nop 0
	global_load_lds_dwordx4 v[248:249], off
	s_mov_b32 m0, s29
	s_nop 0
	global_load_lds_dwordx4 v[250:251], off
	s_waitcnt vmcnt(8)
	s_waitcnt lgkmcnt(0)
	s_barrier
; #define PG8_STAGE(bufoff, gbase, voff) do { _Pragma("unroll") for (int _i = 0; _i < 2; ++_i) \
;         __builtin_amdgcn_global_load_lds((const unsigned*)((const char*)(gbase) + (voff)[_i]), (PG8_LAS unsigned*)(lds + (bufoff) + ldsw + _i * 8192), 16, 0, 0); } while (0)
; #define PG8_LDA(dst, b, h) do { _Pragma("unroll") for (int m = 0; m < 4; ++m) _Pragma("unroll") for (int k = 0; k < 2; ++k) dst[m][k] = *(const PG8_LAS bf16x8*)(lds + PG8_SA(b, h) + aoff + m * 2048 + k * 1024); } while (0)
; #define PG8_LDB(dst, b, h) do { _Pragma("unroll") for (int n = 0; n < 2; ++n) _Pragma("unroll") for (int k = 0; k < 2; ++k) dst[n][k] = *(const PG8_LAS bf16x8*)(lds + PG8_SB(b, h) + boff + n * 2048 + k * 1024); } while (0)
; #define PG8_MMA(ai, bj, At, Bt) do { __builtin_amdgcn_s_setprio(1); _Pragma("unroll") for (int m = 0; m < 4; ++m) _Pragma("unroll") for (int n = 0; n < 2; ++n) _Pragma("unroll") for (int k = 0; k < 2; ++k) \
;         acc[ai][bj][m][n] = __builtin_amdgcn_mfma_f32_16x16x32_bf16(Bt[n][k], At[m][k], acc[ai][bj][m][n], 0, 0, 0); __builtin_amdgcn_s_setprio(0); } while (0)
; #define PG8_WAIT_V(n) asm volatile("s_waitcnt vmcnt(" #n ")" ::: "memory")
; #define PG8_WAIT_L(n) asm volatile("s_waitcnt lgkmcnt(" #n ")" ::: "memory")
; #define PG8_BAR __builtin_amdgcn_s_barrier()
; #define PG8_SCHED __builtin_amdgcn_sched_barrier(0)
; template <class Epi, class Sched, bool ALIGN_EPI = false, bool SP2 = false>
; __device__ __forceinline__ void gemm_phase(PG8_LAS unsigned char* lds, const Gemm g, const Sched& S, const Epi& E) {
;     ...
;             PG8_WAIT_V(8); PG8_WAIT_L(0); PG8_BAR; PG8_MMA(1, 0, At, B0); PG8_MMA(1, 1, At, B1); PG8_BAR; PG8_SCHED;
;             PG8_LDB(B0, 1, 0); PG8_LDB(B1, 1, 1); PG8_SCHED; PG8_LDA(At, 1, 0); PG8_STAGE(PG8_SA(0, 1), a2 + hstep, voffA);
;             PG8_WAIT_V(8); PG8_WAIT_L(0); PG8_BAR; PG8_MMA(0, 0, At, B0); PG8_MMA(0, 1, At, B1); PG8_BAR; PG8_SCHED;
	s_setprio 1
	s_waitcnt lgkmcnt(0)
	v_mfma_f32_16x16x32_bf16 v[64:67], v[184:187], v[216:219], 0
	v_mfma_f32_16x16x32_bf16 v[60:63], v[192:195], v[216:219], 0
	v_mfma_f32_16x16x32_bf16 v[48:51], v[184:187], v[224:227], 0
	v_mfma_f32_16x16x32_bf16 v[44:47], v[192:195], v[224:227], 0
	v_mfma_f32_16x16x32_bf16 v[32:35], v[184:187], v[232:235], 0
	v_mfma_f32_16x16x32_bf16 v[28:31], v[192:195], v[232:235], 0
	v_mfma_f32_16x16x32_bf16 v[16:19], v[184:187], v[240:243], 0
	v_mfma_f32_16x16x32_bf16 v[12:15], v[192:195], v[240:243], 0
	v_mfma_f32_16x16x32_bf16 v[64:67], v[188:191], v[220:223], v[64:67]
	v_mfma_f32_16x16x32_bf16 v[60:63], v[196:199], v[220:223], v[60:63]
	v_mfma_f32_16x16x32_bf16 v[48:51], v[188:191], v[228:231], v[48:51]
	v_mfma_f32_16x16x32_bf16 v[44:47], v[196:199], v[228:231], v[44:47]
	v_mfma_f32_16x16x32_bf16 v[32:35], v[188:191], v[236:239], v[32:35]
	v_mfma_f32_16x16x32_bf16 v[28:31], v[196:199], v[236:239], v[28:31]
	v_mfma_f32_16x16x32_bf16 v[16:19], v[188:191], v[244:247], v[16:19]
	v_mfma_f32_16x16x32_bf16 v[12:15], v[196:199], v[244:247], v[12:15]
	s_setprio 0
	s_setprio 1
	v_mfma_f32_16x16x32_bf16 v[56:59], v[200:203], v[216:219], 0
	v_mfma_f32_16x16x32_bf16 v[52:55], v[208:211], v[216:219], 0
	v_mfma_f32_16x16x32_bf16 v[40:43], v[200:203], v[224:227], 0
	v_mfma_f32_16x16x32_bf16 v[36:39], v[208:211], v[224:227], 0
	v_mfma_f32_16x16x32_bf16 v[24:27], v[200:203], v[232:235], 0
	v_mfma_f32_16x16x32_bf16 v[20:23], v[208:211], v[232:235], 0
	v_mfma_f32_16x16x32_bf16 v[8:11], v[200:203], v[240:243], 0
	v_mfma_f32_16x16x32_bf16 v[4:7], v[208:211], v[240:243], 0
	v_mfma_f32_16x16x32_bf16 v[56:59], v[204:207], v[220:223], v[56:59]
	v_mfma_f32_16x16x32_bf16 v[52:55], v[212:215], v[220:223], v[52:55]
	v_mfma_f32_16x16x32_bf16 v[40:43], v[204:207], v[228:231], v[40:43]
	v_mfma_f32_16x16x32_bf16 v[36:39], v[212:215], v[228:231], v[36:39]
	v_mfma_f32_16x16x32_bf16 v[24:27], v[204:207], v[236:239], v[24:27]
	v_mfma_f32_16x16x32_bf16 v[20:23], v[212:215], v[236:239], v[20:23]
	v_mfma_f32_16x16x32_bf16 v[8:11], v[204:207], v[244:247], v[8:11]
	v_mfma_f32_16x16x32_bf16 v[4:7], v[212:215], v[244:247], v[4:7]
	s_setprio 0
	s_barrier
	s_add_i32 s63, 0, 0x18000
	v_add_u32_e32 v151, s63, v156
	s_add_i32 s64, 0, 0x1c000
	ds_read_b128 v[184:187], v151
	ds_read_b128 v[188:191], v151 offset:1024
	ds_read_b128 v[192:195], v151 offset:2048
	ds_read_b128 v[196:199], v151 offset:3072
	v_add_u32_e32 v151, s64, v156
	ds_read_b128 v[200:203], v151
	ds_read_b128 v[204:207], v151 offset:1024
	ds_read_b128 v[208:211], v151 offset:2048
	ds_read_b128 v[212:215], v151 offset:3072
	s_add_u32 s22, s22, 0x80000
	s_addc_u32 s23, s23, 0
	s_mov_b32 m0, s30
	ds_read_b128 v[216:219], v160 offset:32768
	ds_read_b128 v[220:223], v160 offset:33792
	ds_read_b128 v[224:227], v160 offset:34816
	ds_read_b128 v[228:231], v160 offset:35840
	ds_read_b128 v[232:235], v160 offset:36864
	ds_read_b128 v[236:239], v160 offset:37888
	ds_read_b128 v[240:243], v160 offset:38912
	ds_read_b128 v[244:247], v160 offset:39936
	global_load_lds_dwordx4 v134, s[22:23]
	s_mov_b32 m0, s31
	s_nop 0
	global_load_lds_dwordx4 v132, s[22:23]
	s_waitcnt vmcnt(8)
	s_waitcnt lgkmcnt(0)
	s_barrier
	s_setprio 1
	s_waitcnt lgkmcnt(0)
	v_mfma_f32_16x16x32_bf16 v[128:131], v[184:187], v[216:219], v[128:131]
	v_mfma_f32_16x16x32_bf16 v[124:127], v[192:195], v[216:219], v[124:127]
	v_mfma_f32_16x16x32_bf16 v[112:115], v[184:187], v[224:227], v[112:115]
	v_mfma_f32_16x16x32_bf16 v[108:111], v[192:195], v[224:227], v[108:111]
	v_mfma_f32_16x16x32_bf16 v[96:99], v[184:187], v[232:235], v[96:99]
	v_mfma_f32_16x16x32_bf16 v[92:95], v[192:195], v[232:235], v[92:95]
	v_mfma_f32_16x16x32_bf16 v[80:83], v[184:187], v[240:243], v[80:83]
	v_mfma_f32_16x16x32_bf16 v[76:79], v[192:195], v[240:243], v[76:79]
	v_mfma_f32_16x16x32_bf16 v[128:131], v[188:191], v[220:223], v[128:131]
	v_mfma_f32_16x16x32_bf16 v[124:127], v[196:199], v[220:223], v[124:127]
	v_mfma_f32_16x16x32_bf16 v[112:115], v[188:191], v[228:231], v[112:115]
	v_mfma_f32_16x16x32_bf16 v[108:111], v[196:199], v[228:231], v[108:111]
	v_mfma_f32_16x16x32_bf16 v[96:99], v[188:191], v[236:239], v[96:99]
	v_mfma_f32_16x16x32_bf16 v[92:95], v[196:199], v[236:239], v[92:95]
	v_mfma_f32_16x16x32_bf16 v[80:83], v[188:191], v[244:247], v[80:83]
	v_mfma_f32_16x16x32_bf16 v[76:79], v[196:199], v[244:247], v[76:79]
	s_setprio 0
	s_setprio 1
	v_mfma_f32_16x16x32_bf16 v[120:123], v[200:203], v[216:219], v[120:123]
	v_mfma_f32_16x16x32_bf16 v[116:119], v[208:211], v[216:219], v[116:119]
	v_mfma_f32_16x16x32_bf16 v[104:107], v[200:203], v[224:227], v[104:107]
	v_mfma_f32_16x16x32_bf16 v[100:103], v[208:211], v[224:227], v[100:103]
	v_mfma_f32_16x16x32_bf16 v[88:91], v[200:203], v[232:235], v[88:91]
	v_mfma_f32_16x16x32_bf16 v[84:87], v[208:211], v[232:235], v[84:87]
	v_mfma_f32_16x16x32_bf16 v[72:75], v[200:203], v[240:243], v[72:75]
	v_mfma_f32_16x16x32_bf16 v[68:71], v[208:211], v[240:243], v[68:71]
	v_mfma_f32_16x16x32_bf16 v[120:123], v[204:207], v[220:223], v[120:123]
	v_mfma_f32_16x16x32_bf16 v[116:119], v[212:215], v[220:223], v[116:119]
	v_mfma_f32_16x16x32_bf16 v[104:107], v[204:207], v[228:231], v[104:107]
	v_mfma_f32_16x16x32_bf16 v[100:103], v[212:215], v[228:231], v[100:103]
	v_mfma_f32_16x16x32_bf16 v[88:91], v[204:207], v[236:239], v[88:91]
	v_mfma_f32_16x16x32_bf16 v[84:87], v[212:215], v[236:239], v[84:87]
	v_mfma_f32_16x16x32_bf16 v[72:75], v[204:207], v[244:247], v[72:75]
	v_mfma_f32_16x16x32_bf16 v[68:71], v[212:215], v[244:247], v[68:71]
	s_setprio 0
	s_barrier
; #define PG8_STAGE(bufoff, gbase, voff) do { _Pragma("unroll") for (int _i = 0; _i < 2; ++_i) \
;         __builtin_amdgcn_global_load_lds((const unsigned*)((const char*)(gbase) + (voff)[_i]), (PG8_LAS unsigned*)(lds + (bufoff) + ldsw + _i * 8192), 16, 0, 0); } while (0)
; #define PG8_LDA(dst, b, h) do { _Pragma("unroll") for (int m = 0; m < 4; ++m) _Pragma("unroll") for (int k = 0; k < 2; ++k) dst[m][k] = *(const PG8_LAS bf16x8*)(lds + PG8_SA(b, h) + aoff + m * 2048 + k * 1024); } while (0)
; #define PG8_MMA(ai, bj, At, Bt) do { __builtin_amdgcn_s_setprio(1); _Pragma("unroll") for (int m = 0; m < 4; ++m) _Pragma("unroll") for (int n = 0; n < 2; ++n) _Pragma("unroll") for (int k = 0; k < 2; ++k) \
;         acc[ai][bj][m][n] = __builtin_amdgcn_mfma_f32_16x16x32_bf16(Bt[n][k], At[m][k], acc[ai][bj][m][n], 0, 0, 0); __builtin_amdgcn_s_setprio(0); } while (0)
; #define PG8_WAIT_V(n) asm volatile("s_waitcnt vmcnt(" #n ")" ::: "memory")
; #define PG8_WAIT_L(n) asm volatile("s_waitcnt lgkmcnt(" #n ")" ::: "memory")
; #define PG8_BAR __builtin_amdgcn_s_barrier()
; #define PG8_SCHED __builtin_amdgcn_sched_barrier(0)
; template <class Epi, class Sched, bool ALIGN_EPI = false, bool SP2 = false>
; __device__ __forceinline__ void gemm_phase(PG8_LAS unsigned char* lds, const Gemm g, const Sched& S, const Epi& E) {
;     ...
;             PG8_LDA(At, 1, 1); PG8_STAGE(PG8_SB(1, 0), b3, voffB); PG8_STAGE(PG8_SB(1, 1), b3 + hstep, voffB); PG8_STAGE(PG8_SA(1, 0), a3, voffA);
;             PG8_WAIT_V(8); PG8_WAIT_L(0); PG8_BAR; PG8_MMA(1, 0, At, B0); PG8_MMA(1, 1, At, B1); PG8_BAR; PG8_SCHED;
	s_add_i32 s22, s63, s27
	s_mov_b32 m0, s22
	ds_read_b128 v[216:219], v160 offset:49152
	ds_read_b128 v[220:223], v160 offset:50176
	ds_read_b128 v[224:227], v160 offset:51200
	ds_read_b128 v[228:231], v160 offset:52224
	ds_read_b128 v[232:235], v160 offset:53248
	ds_read_b128 v[236:239], v160 offset:54272
	ds_read_b128 v[240:243], v160 offset:55296
	ds_read_b128 v[244:247], v160 offset:56320
	s_add_u32 vcc_lo, s20, 0x80
	s_addc_u32 vcc_hi, s21, 0
	global_load_lds_dwordx4 v2, vcc
	s_add_i32 m0, s22, 0x2000
	s_add_u32 s20, s20, 0x80080
	s_addc_u32 s21, s21, 0
	s_add_i32 s22, s64, s27
	s_add_u32 vcc_lo, s20, 0xfff80000
	s_addc_u32 vcc_hi, s21, -1
	global_load_lds_dwordx4 v0, vcc
	s_mov_b32 m0, s22
	s_nop 0
	global_load_lds_dwordx4 v2, s[20:21]
	s_add_i32 m0, s22, 0x2000
	s_nop 0
	global_load_lds_dwordx4 v0, s[20:21]
	v_lshl_add_u64 v[152:153], v[248:249], 0, s[36:37]
	s_mov_b32 m0, s34
	s_nop 0
	global_load_lds_dwordx4 v[152:153], off
	v_lshl_add_u64 v[152:153], v[250:251], 0, s[36:37]
	s_mov_b32 m0, s35
	s_nop 0
	global_load_lds_dwordx4 v[152:153], off
	s_waitcnt vmcnt(8)
	s_waitcnt lgkmcnt(0)
	s_barrier
	s_setprio 1
	s_waitcnt lgkmcnt(0)
	v_mfma_f32_16x16x32_bf16 v[64:67], v[184:187], v[216:219], v[64:67]
	v_mfma_f32_16x16x32_bf16 v[60:63], v[192:195], v[216:219], v[60:63]
	v_mfma_f32_16x16x32_bf16 v[48:51], v[184:187], v[224:227], v[48:51]
	v_mfma_f32_16x16x32_bf16 v[44:47], v[192:195], v[224:227], v[44:47]
	v_mfma_f32_16x16x32_bf16 v[32:35], v[184:187], v[232:235], v[32:35]
	v_mfma_f32_16x16x32_bf16 v[28:31], v[192:195], v[232:235], v[28:31]
	v_mfma_f32_16x16x32_bf16 v[16:19], v[184:187], v[240:243], v[16:19]
	v_mfma_f32_16x16x32_bf16 v[12:15], v[192:195], v[240:243], v[12:15]
	v_mfma_f32_16x16x32_bf16 v[64:67], v[188:191], v[220:223], v[64:67]
	v_mfma_f32_16x16x32_bf16 v[60:63], v[196:199], v[220:223], v[60:63]
	v_mfma_f32_16x16x32_bf16 v[48:51], v[188:191], v[228:231], v[48:51]
	v_mfma_f32_16x16x32_bf16 v[44:47], v[196:199], v[228:231], v[44:47]
	v_mfma_f32_16x16x32_bf16 v[32:35], v[188:191], v[236:239], v[32:35]
	v_mfma_f32_16x16x32_bf16 v[28:31], v[196:199], v[236:239], v[28:31]
	v_mfma_f32_16x16x32_bf16 v[16:19], v[188:191], v[244:247], v[16:19]
	v_mfma_f32_16x16x32_bf16 v[12:15], v[196:199], v[244:247], v[12:15]
	s_setprio 0
	s_setprio 1
	v_mfma_f32_16x16x32_bf16 v[56:59], v[200:203], v[216:219], v[56:59]
	v_mfma_f32_16x16x32_bf16 v[52:55], v[208:211], v[216:219], v[52:55]
	v_mfma_f32_16x16x32_bf16 v[40:43], v[200:203], v[224:227], v[40:43]
	v_mfma_f32_16x16x32_bf16 v[36:39], v[208:211], v[224:227], v[36:39]
	v_mfma_f32_16x16x32_bf16 v[24:27], v[200:203], v[232:235], v[24:27]
	v_mfma_f32_16x16x32_bf16 v[20:23], v[208:211], v[232:235], v[20:23]
	v_mfma_f32_16x16x32_bf16 v[8:11], v[200:203], v[240:243], v[8:11]
	v_mfma_f32_16x16x32_bf16 v[4:7], v[208:211], v[240:243], v[4:7]
	v_mfma_f32_16x16x32_bf16 v[56:59], v[204:207], v[220:223], v[56:59]
	v_mfma_f32_16x16x32_bf16 v[52:55], v[212:215], v[220:223], v[52:55]
	v_mfma_f32_16x16x32_bf16 v[40:43], v[204:207], v[228:231], v[40:43]
	v_mfma_f32_16x16x32_bf16 v[36:39], v[212:215], v[228:231], v[36:39]
	v_mfma_f32_16x16x32_bf16 v[24:27], v[204:207], v[236:239], v[24:27]
	v_mfma_f32_16x16x32_bf16 v[20:23], v[212:215], v[236:239], v[20:23]
	v_mfma_f32_16x16x32_bf16 v[8:11], v[204:207], v[244:247], v[8:11]
	v_mfma_f32_16x16x32_bf16 v[4:7], v[212:215], v[244:247], v[4:7]
	s_setprio 0
	s_barrier
	s_add_i32 s57, s57, 2
	s_add_u32 s18, s18, 0x100
	s_addc_u32 s19, s19, 0
	s_add_u32 s51, s51, 0x100
	s_addc_u32 s56, s56, 0
	s_cmp_gt_u32 s57, 29

; #define PG8_STAGE(bufoff, gbase, voff) do { _Pragma("unroll") for (int _i = 0; _i < 2; ++_i) \
;         __builtin_amdgcn_global_load_lds((const unsigned*)((const char*)(gbase) + (voff)[_i]), (PG8_LAS unsigned*)(lds + (bufoff) + ldsw + _i * 8192), 16, 0, 0); } while (0)
; #define PG8_LDA(dst, b, h) do { _Pragma("unroll") for (int m = 0; m < 4; ++m) _Pragma("unroll") for (int k = 0; k < 2; ++k) dst[m][k] = *(const PG8_LAS bf16x8*)(lds + PG8_SA(b, h) + aoff + m * 2048 + k * 1024); } while (0)
; #define PG8_LDB(dst, b, h) do { _Pragma("unroll") for (int n = 0; n < 2; ++n) _Pragma("unroll") for (int k = 0; k < 2; ++k) dst[n][k] = *(const PG8_LAS bf16x8*)(lds + PG8_SB(b, h) + boff + n * 2048 + k * 1024); } while (0)
; #define PG8_MMA(ai, bj, At, Bt) do { __builtin_amdgcn_s_setprio(1); _Pragma("unroll") for (int m = 0; m < 4; ++m) _Pragma("unroll") for (int n = 0; n < 2; ++n) _Pragma("unroll") for (int k = 0; k < 2; ++k) \
;         acc[ai][bj][m][n] = __builtin_amdgcn_mfma_f32_16x16x32_bf16(Bt[n][k], At[m][k], acc[ai][bj][m][n], 0, 0, 0); __builtin_amdgcn_s_setprio(0); } while (0)
; #define PG8_WAIT_V(n) asm volatile("s_waitcnt vmcnt(" #n ")" ::: "memory")
; template <class Epi, class Sched, bool ALIGN_EPI = false, bool SP2 = false>
; __device__ __forceinline__ void gemm_phase(PG8_LAS unsigned char* lds, const Gemm g, const Sched& S, const Epi& E) {
;     ...
;         const char* nA = has_next ? (const char*)g.A + (size_t)nxt.pm * tstep : cA; const char* nB = has_next ? (const char*)g.Bt + (size_t)nxt.pn * tstep : cB;
;         for (int t = 0; t < nt; t += 2) {
;             const bool last = (t == nt - 2);
;             const char* a1 = cA + (size_t)(t + 1) * kstep;
;             const char* a2 = last ? nA : cA + (size_t)(t + 2) * kstep; const char* b2 = last ? nB : cB + (size_t)(t + 2) * kstep;
;             const char* a3 = a2 + kstep; const char* b3 = b2 + kstep;
;             if (last && has_next) S.a_ready(nxt);
;             if constexpr (SP2) {
;             PG8_LDB(B0, 0, 0); PG8_LDB(B1, 0, 1); PG8_SCHED; PG8_LDA(At, 0, 0); PG8_STAGE(PG8_SA(1, 1), a1 + hstep, voffA);
;             PG8_WAIT_V(8); PG8_WAIT_L(0); PG8_BAR; PG8_MMA(0, 0, At, B0); PG8_MMA(0, 1, At, B1); PG8_BAR; PG8_SCHED;
;             PG8_LDA(At, 0, 1); PG8_STAGE(PG8_SB(0, 0), b2, voffB); PG8_STAGE(PG8_SB(0, 1), b2 + hstep, voffB); PG8_STAGE(PG8_SA(0, 0), a2, voffA);
.LBB0_482:
	s_ashr_i32 s13, s12, 31
	s_lshl_b64 s[14:15], s[12:13], 20
	s_add_u32 s14, s54, s14
	s_addc_u32 s15, s55, s15
	s_and_b64 s[16:17], s[4:5], exec
	s_cselect_b32 s13, s15, s23
	s_cselect_b32 s19, s14, s22
	s_ashr_i32 s11, s10, 31
	s_lshl_b64 s[16:17], s[10:11], 20
	s_add_u32 s16, s29, s16
	s_addc_u32 s17, s30, s17
	s_and_b64 s[26:27], s[4:5], exec
	s_cselect_b32 s11, s17, s25
	s_cselect_b32 s56, s16, s24
	s_add_u32 s22, s22, 0x80080
	s_addc_u32 s23, s23, 0
	s_add_u32 s57, s24, 0x100
	s_addc_u32 s63, s25, 0
	s_mov_b32 s64, -2
	s_waitcnt lgkmcnt(0)
	s_add_u32 s24, s22, 0xfff80080
	s_addc_u32 s25, s23, -1
	s_add_i32 s65, 0, 0x10000
	s_cmp_eq_u32 s64, 28
	s_cselect_b32 s27, s13, s25
	s_cselect_b32 s26, s19, s24
	s_cselect_b32 s25, s11, s63
	s_cselect_b32 s24, s56, s57
	s_add_i32 s76, 0, 0x14000
	v_add_u32_e32 v162, s65, v185
	v_add_u32_e32 v166, s76, v185
	ds_read_b128 v[132:135], v162
	ds_read_b128 v[136:139], v162 offset:1024
	ds_read_b128 v[158:161], v162 offset:2048
	ds_read_b128 v[162:165], v162 offset:3072
	ds_read_b128 v[188:191], v166
	ds_read_b128 v[192:195], v166 offset:1024
	ds_read_b128 v[196:199], v166 offset:2048
	ds_read_b128 v[200:203], v166 offset:3072
	s_add_i32 m0, s21, 0xc000
	ds_read_b128 v[204:207], v187
	ds_read_b128 v[208:211], v187 offset:1024
	ds_read_b128 v[212:215], v187 offset:2048
	ds_read_b128 v[216:219], v187 offset:3072
	ds_read_b128 v[220:223], v187 offset:4096
	ds_read_b128 v[224:227], v187 offset:5120
	ds_read_b128 v[228:231], v187 offset:6144
	ds_read_b128 v[232:235], v187 offset:7168
	global_load_lds_dwordx4 v154, s[22:23]
	s_add_i32 m0, s21, 0xe000
	s_nop 0
	global_load_lds_dwordx4 v156, s[22:23]
	s_waitcnt vmcnt(8)
	s_waitcnt lgkmcnt(0)
	s_barrier
	s_setprio 1
	s_waitcnt lgkmcnt(0)
	v_mfma_f32_16x16x32_bf16 v[128:131], v[132:135], v[204:207], 0
	v_mfma_f32_16x16x32_bf16 v[124:127], v[158:161], v[204:207], 0
	v_mfma_f32_16x16x32_bf16 v[112:115], v[132:135], v[212:215], 0
	v_mfma_f32_16x16x32_bf16 v[108:111], v[158:161], v[212:215], 0
	v_mfma_f32_16x16x32_bf16 v[96:99], v[132:135], v[220:223], 0
	v_mfma_f32_16x16x32_bf16 v[92:95], v[158:161], v[220:223], 0
	v_mfma_f32_16x16x32_bf16 v[80:83], v[132:135], v[228:231], 0
	v_mfma_f32_16x16x32_bf16 v[76:79], v[158:161], v[228:231], 0
	v_mfma_f32_16x16x32_bf16 v[128:131], v[136:139], v[208:211], v[128:131]
	v_mfma_f32_16x16x32_bf16 v[124:127], v[162:165], v[208:211], v[124:127]
	v_mfma_f32_16x16x32_bf16 v[112:115], v[136:139], v[216:219], v[112:115]
	v_mfma_f32_16x16x32_bf16 v[108:111], v[162:165], v[216:219], v[108:111]
	v_mfma_f32_16x16x32_bf16 v[96:99], v[136:139], v[224:227], v[96:99]
	v_mfma_f32_16x16x32_bf16 v[92:95], v[162:165], v[224:227], v[92:95]
	v_mfma_f32_16x16x32_bf16 v[80:83], v[136:139], v[232:235], v[80:83]
	v_mfma_f32_16x16x32_bf16 v[76:79], v[162:165], v[232:235], v[76:79]
	s_setprio 0
	s_setprio 1
	v_mfma_f32_16x16x32_bf16 v[120:123], v[188:191], v[204:207], 0
	v_mfma_f32_16x16x32_bf16 v[116:119], v[196:199], v[204:207], 0
	v_mfma_f32_16x16x32_bf16 v[104:107], v[188:191], v[212:215], 0
	v_mfma_f32_16x16x32_bf16 v[100:103], v[196:199], v[212:215], 0
	v_mfma_f32_16x16x32_bf16 v[88:91], v[188:191], v[220:223], 0
	v_mfma_f32_16x16x32_bf16 v[84:87], v[196:199], v[220:223], 0
	v_mfma_f32_16x16x32_bf16 v[72:75], v[188:191], v[228:231], 0
	v_mfma_f32_16x16x32_bf16 v[68:71], v[196:199], v[228:231], 0
	v_mfma_f32_16x16x32_bf16 v[120:123], v[192:195], v[208:211], v[120:123]
	v_mfma_f32_16x16x32_bf16 v[116:119], v[200:203], v[208:211], v[116:119]
	v_mfma_f32_16x16x32_bf16 v[104:107], v[192:195], v[216:219], v[104:107]
	v_mfma_f32_16x16x32_bf16 v[100:103], v[200:203], v[216:219], v[100:103]
	v_mfma_f32_16x16x32_bf16 v[88:91], v[192:195], v[224:227], v[88:91]
	v_mfma_f32_16x16x32_bf16 v[84:87], v[200:203], v[224:227], v[84:87]
	v_mfma_f32_16x16x32_bf16 v[72:75], v[192:195], v[232:235], v[72:75]
	v_mfma_f32_16x16x32_bf16 v[68:71], v[200:203], v[232:235], v[68:71]
	s_setprio 0
	s_barrier
	s_add_i32 s65, s65, s31
	s_mov_b32 m0, s65
	ds_read_b128 v[204:207], v187 offset:16384
	ds_read_b128 v[208:211], v187 offset:17408
	ds_read_b128 v[212:215], v187 offset:18432
	ds_read_b128 v[216:219], v187 offset:19456
	ds_read_b128 v[220:223], v187 offset:20480
	ds_read_b128 v[224:227], v187 offset:21504
	ds_read_b128 v[228:231], v187 offset:22528
	ds_read_b128 v[232:235], v187 offset:23552
	global_load_lds_dwordx4 v2, s[24:25]
	s_add_i32 m0, s65, 0x2000
	s_add_u32 s66, s24, 0x80000
	s_addc_u32 s67, s25, 0
	s_add_i32 s65, s76, s31
	global_load_lds_dwordx4 v152, s[24:25]
	s_mov_b32 m0, s65
	v_lshl_add_u64 v[240:241], s[26:27], 0, v[150:151]
	global_load_lds_dwordx4 v2, s[66:67]
	s_add_i32 m0, s65, 0x2000
	s_nop 0
	global_load_lds_dwordx4 v152, s[66:67]
	v_lshl_add_u64 v[238:239], s[26:27], 0, v[0:1]
	s_mov_b32 m0, s21
	s_nop 0
	global_load_lds_dwordx4 v[238:239], off
	s_mov_b32 m0, s34
	s_nop 0
	global_load_lds_dwordx4 v[240:241], off
	s_waitcnt vmcnt(8)
	s_waitcnt lgkmcnt(0)
	s_barrier
; #define PG8_STAGE(bufoff, gbase, voff) do { _Pragma("unroll") for (int _i = 0; _i < 2; ++_i) \
;         __builtin_amdgcn_global_load_lds((const unsigned*)((const char*)(gbase) + (voff)[_i]), (PG8_LAS unsigned*)(lds + (bufoff) + ldsw + _i * 8192), 16, 0, 0); } while (0)
; #define PG8_LDA(dst, b, h) do { _Pragma("unroll") for (int m = 0; m < 4; ++m) _Pragma("unroll") for (int k = 0; k < 2; ++k) dst[m][k] = *(const PG8_LAS bf16x8*)(lds + PG8_SA(b, h) + aoff + m * 2048 + k * 1024); } while (0)
; #define PG8_LDB(dst, b, h) do { _Pragma("unroll") for (int n = 0; n < 2; ++n) _Pragma("unroll") for (int k = 0; k < 2; ++k) dst[n][k] = *(const PG8_LAS bf16x8*)(lds + PG8_SB(b, h) + boff + n * 2048 + k * 1024); } while (0)
; #define PG8_MMA(ai, bj, At, Bt) do { __builtin_amdgcn_s_setprio(1); _Pragma("unroll") for (int m = 0; m < 4; ++m) _Pragma("unroll") for (int n = 0; n < 2; ++n) _Pragma("unroll") for (int k = 0; k < 2; ++k) \
;         acc[ai][bj][m][n] = __builtin_amdgcn_mfma_f32_16x16x32_bf16(Bt[n][k], At[m][k], acc[ai][bj][m][n], 0, 0, 0); __builtin_amdgcn_s_setprio(0); } while (0)
; #define PG8_WAIT_V(n) asm volatile("s_waitcnt vmcnt(" #n ")" ::: "memory")
; #define PG8_WAIT_L(n) asm volatile("s_waitcnt lgkmcnt(" #n ")" ::: "memory")
; #define PG8_BAR __builtin_amdgcn_s_barrier()
; #define PG8_SCHED __builtin_amdgcn_sched_barrier(0)
; template <class Epi, class Sched, bool ALIGN_EPI = false, bool SP2 = false>
; __device__ __forceinline__ void gemm_phase(PG8_LAS unsigned char* lds, const Gemm g, const Sched& S, const Epi& E) {
;     ...
;             PG8_WAIT_V(8); PG8_WAIT_L(0); PG8_BAR; PG8_MMA(1, 0, At, B0); PG8_MMA(1, 1, At, B1); PG8_BAR; PG8_SCHED;
;             PG8_LDB(B0, 1, 0); PG8_LDB(B1, 1, 1); PG8_SCHED; PG8_LDA(At, 1, 0); PG8_STAGE(PG8_SA(0, 1), a2 + hstep, voffA);
;             PG8_WAIT_V(8); PG8_WAIT_L(0); PG8_BAR; PG8_MMA(0, 0, At, B0); PG8_MMA(0, 1, At, B1); PG8_BAR; PG8_SCHED;
	s_setprio 1
	s_waitcnt lgkmcnt(0)
	v_mfma_f32_16x16x32_bf16 v[64:67], v[132:135], v[204:207], 0
	v_mfma_f32_16x16x32_bf16 v[60:63], v[158:161], v[204:207], 0
	v_mfma_f32_16x16x32_bf16 v[48:51], v[132:135], v[212:215], 0
	v_mfma_f32_16x16x32_bf16 v[44:47], v[158:161], v[212:215], 0
	v_mfma_f32_16x16x32_bf16 v[32:35], v[132:135], v[220:223], 0
	v_mfma_f32_16x16x32_bf16 v[28:31], v[158:161], v[220:223], 0
	v_mfma_f32_16x16x32_bf16 v[16:19], v[132:135], v[228:231], 0
	v_mfma_f32_16x16x32_bf16 v[12:15], v[158:161], v[228:231], 0
	v_mfma_f32_16x16x32_bf16 v[64:67], v[136:139], v[208:211], v[64:67]
	v_mfma_f32_16x16x32_bf16 v[60:63], v[162:165], v[208:211], v[60:63]
	v_mfma_f32_16x16x32_bf16 v[48:51], v[136:139], v[216:219], v[48:51]
	v_mfma_f32_16x16x32_bf16 v[44:47], v[162:165], v[216:219], v[44:47]
	v_mfma_f32_16x16x32_bf16 v[32:35], v[136:139], v[224:227], v[32:35]
	v_mfma_f32_16x16x32_bf16 v[28:31], v[162:165], v[224:227], v[28:31]
	v_mfma_f32_16x16x32_bf16 v[16:19], v[136:139], v[232:235], v[16:19]
	v_mfma_f32_16x16x32_bf16 v[12:15], v[162:165], v[232:235], v[12:15]
	s_setprio 0
	s_setprio 1
	v_mfma_f32_16x16x32_bf16 v[56:59], v[188:191], v[204:207], 0
	v_mfma_f32_16x16x32_bf16 v[52:55], v[196:199], v[204:207], 0
	v_mfma_f32_16x16x32_bf16 v[40:43], v[188:191], v[212:215], 0
	v_mfma_f32_16x16x32_bf16 v[36:39], v[196:199], v[212:215], 0
	v_mfma_f32_16x16x32_bf16 v[24:27], v[188:191], v[220:223], 0
	v_mfma_f32_16x16x32_bf16 v[20:23], v[196:199], v[220:223], 0
	v_mfma_f32_16x16x32_bf16 v[8:11], v[188:191], v[228:231], 0
	v_mfma_f32_16x16x32_bf16 v[4:7], v[196:199], v[228:231], 0
	v_mfma_f32_16x16x32_bf16 v[56:59], v[192:195], v[208:211], v[56:59]
	v_mfma_f32_16x16x32_bf16 v[52:55], v[200:203], v[208:211], v[52:55]
	v_mfma_f32_16x16x32_bf16 v[40:43], v[192:195], v[216:219], v[40:43]
	v_mfma_f32_16x16x32_bf16 v[36:39], v[200:203], v[216:219], v[36:39]
	v_mfma_f32_16x16x32_bf16 v[24:27], v[192:195], v[224:227], v[24:27]
	v_mfma_f32_16x16x32_bf16 v[20:23], v[200:203], v[224:227], v[20:23]
	v_mfma_f32_16x16x32_bf16 v[8:11], v[192:195], v[232:235], v[8:11]
	v_mfma_f32_16x16x32_bf16 v[4:7], v[200:203], v[232:235], v[4:7]
	s_setprio 0
	s_barrier
	s_add_i32 s65, 0, 0x18000
	s_add_i32 s66, 0, 0x1c000
	v_add_u32_e32 v162, s65, v185
	v_add_u32_e32 v200, s66, v185
	ds_read_b128 v[132:135], v162
	ds_read_b128 v[136:139], v162 offset:1024
	ds_read_b128 v[158:161], v162 offset:2048
	ds_read_b128 v[162:165], v162 offset:3072
	ds_read_b128 v[188:191], v200
	ds_read_b128 v[192:195], v200 offset:1024
	ds_read_b128 v[196:199], v200 offset:2048
	ds_read_b128 v[200:203], v200 offset:3072
	s_add_u32 s26, s26, 0x80000
	s_addc_u32 s27, s27, 0
	s_mov_b32 m0, s35
	ds_read_b128 v[204:207], v187 offset:32768
	ds_read_b128 v[208:211], v187 offset:33792
	ds_read_b128 v[212:215], v187 offset:34816
	ds_read_b128 v[216:219], v187 offset:35840
	ds_read_b128 v[220:223], v187 offset:36864
	ds_read_b128 v[224:227], v187 offset:37888
	ds_read_b128 v[228:231], v187 offset:38912
	ds_read_b128 v[232:235], v187 offset:39936
	global_load_lds_dwordx4 v0, s[26:27]
	s_mov_b32 m0, s42
	s_nop 0
	global_load_lds_dwordx4 v150, s[26:27]
	s_waitcnt vmcnt(8)
	s_waitcnt lgkmcnt(0)
	s_barrier
	s_setprio 1
	s_waitcnt lgkmcnt(0)
	v_mfma_f32_16x16x32_bf16 v[128:131], v[132:135], v[204:207], v[128:131]
	v_mfma_f32_16x16x32_bf16 v[124:127], v[158:161], v[204:207], v[124:127]
	v_mfma_f32_16x16x32_bf16 v[112:115], v[132:135], v[212:215], v[112:115]
	v_mfma_f32_16x16x32_bf16 v[108:111], v[158:161], v[212:215], v[108:111]
	v_mfma_f32_16x16x32_bf16 v[96:99], v[132:135], v[220:223], v[96:99]
	v_mfma_f32_16x16x32_bf16 v[92:95], v[158:161], v[220:223], v[92:95]
	v_mfma_f32_16x16x32_bf16 v[80:83], v[132:135], v[228:231], v[80:83]
	v_mfma_f32_16x16x32_bf16 v[76:79], v[158:161], v[228:231], v[76:79]
	v_mfma_f32_16x16x32_bf16 v[128:131], v[136:139], v[208:211], v[128:131]
	v_mfma_f32_16x16x32_bf16 v[124:127], v[162:165], v[208:211], v[124:127]
	v_mfma_f32_16x16x32_bf16 v[112:115], v[136:139], v[216:219], v[112:115]
	v_mfma_f32_16x16x32_bf16 v[108:111], v[162:165], v[216:219], v[108:111]
	v_mfma_f32_16x16x32_bf16 v[96:99], v[136:139], v[224:227], v[96:99]
	v_mfma_f32_16x16x32_bf16 v[92:95], v[162:165], v[224:227], v[92:95]
	v_mfma_f32_16x16x32_bf16 v[80:83], v[136:139], v[232:235], v[80:83]
	v_mfma_f32_16x16x32_bf16 v[76:79], v[162:165], v[232:235], v[76:79]
	s_setprio 0
	s_setprio 1
	v_mfma_f32_16x16x32_bf16 v[120:123], v[188:191], v[204:207], v[120:123]
	v_mfma_f32_16x16x32_bf16 v[116:119], v[196:199], v[204:207], v[116:119]
	v_mfma_f32_16x16x32_bf16 v[104:107], v[188:191], v[212:215], v[104:107]
	v_mfma_f32_16x16x32_bf16 v[100:103], v[196:199], v[212:215], v[100:103]
	v_mfma_f32_16x16x32_bf16 v[88:91], v[188:191], v[220:223], v[88:91]
	v_mfma_f32_16x16x32_bf16 v[84:87], v[196:199], v[220:223], v[84:87]
	v_mfma_f32_16x16x32_bf16 v[72:75], v[188:191], v[228:231], v[72:75]
	v_mfma_f32_16x16x32_bf16 v[68:71], v[196:199], v[228:231], v[68:71]
	v_mfma_f32_16x16x32_bf16 v[120:123], v[192:195], v[208:211], v[120:123]
	v_mfma_f32_16x16x32_bf16 v[116:119], v[200:203], v[208:211], v[116:119]
	v_mfma_f32_16x16x32_bf16 v[104:107], v[192:195], v[216:219], v[104:107]
	v_mfma_f32_16x16x32_bf16 v[100:103], v[200:203], v[216:219], v[100:103]
	v_mfma_f32_16x16x32_bf16 v[88:91], v[192:195], v[224:227], v[88:91]
	v_mfma_f32_16x16x32_bf16 v[84:87], v[200:203], v[224:227], v[84:87]
	v_mfma_f32_16x16x32_bf16 v[72:75], v[192:195], v[232:235], v[72:75]
	v_mfma_f32_16x16x32_bf16 v[68:71], v[200:203], v[232:235], v[68:71]
	s_setprio 0
	s_barrier
; #define PG8_STAGE(bufoff, gbase, voff) do { _Pragma("unroll") for (int _i = 0; _i < 2; ++_i) \
;         __builtin_amdgcn_global_load_lds((const unsigned*)((const char*)(gbase) + (voff)[_i]), (PG8_LAS unsigned*)(lds + (bufoff) + ldsw + _i * 8192), 16, 0, 0); } while (0)
; #define PG8_LDA(dst, b, h) do { _Pragma("unroll") for (int m = 0; m < 4; ++m) _Pragma("unroll") for (int k = 0; k < 2; ++k) dst[m][k] = *(const PG8_LAS bf16x8*)(lds + PG8_SA(b, h) + aoff + m * 2048 + k * 1024); } while (0)
; #define PG8_MMA(ai, bj, At, Bt) do { __builtin_amdgcn_s_setprio(1); _Pragma("unroll") for (int m = 0; m < 4; ++m) _Pragma("unroll") for (int n = 0; n < 2; ++n) _Pragma("unroll") for (int k = 0; k < 2; ++k) \
;         acc[ai][bj][m][n] = __builtin_amdgcn_mfma_f32_16x16x32_bf16(Bt[n][k], At[m][k], acc[ai][bj][m][n], 0, 0, 0); __builtin_amdgcn_s_setprio(0); } while (0)
; #define PG8_WAIT_V(n) asm volatile("s_waitcnt vmcnt(" #n ")" ::: "memory")
; #define PG8_WAIT_L(n) asm volatile("s_waitcnt lgkmcnt(" #n ")" ::: "memory")
; #define PG8_BAR __builtin_amdgcn_s_barrier()
; #define PG8_SCHED __builtin_amdgcn_sched_barrier(0)
; template <class Epi, class Sched, bool ALIGN_EPI = false, bool SP2 = false>
; __device__ __forceinline__ void gemm_phase(PG8_LAS unsigned char* lds, const Gemm g, const Sched& S, const Epi& E) {
;     ...
;             PG8_LDA(At, 1, 1); PG8_STAGE(PG8_SB(1, 0), b3, voffB); PG8_STAGE(PG8_SB(1, 1), b3 + hstep, voffB); PG8_STAGE(PG8_SA(1, 0), a3, voffA);
;             PG8_WAIT_V(8); PG8_WAIT_L(0); PG8_BAR; PG8_MMA(1, 0, At, B0); PG8_MMA(1, 1, At, B1); PG8_BAR; PG8_SCHED;
	s_add_i32 s26, s65, s31
	s_mov_b32 m0, s26
	ds_read_b128 v[204:207], v187 offset:49152
	ds_read_b128 v[208:211], v187 offset:50176
	ds_read_b128 v[212:215], v187 offset:51200
	ds_read_b128 v[216:219], v187 offset:52224
	ds_read_b128 v[220:223], v187 offset:53248
	ds_read_b128 v[224:227], v187 offset:54272
	ds_read_b128 v[228:231], v187 offset:55296
	ds_read_b128 v[232:235], v187 offset:56320
	s_add_u32 vcc_lo, s24, 0x80
	s_addc_u32 vcc_hi, s25, 0
	global_load_lds_dwordx4 v2, vcc
	s_add_i32 m0, s26, 0x2000
	s_add_u32 s24, s24, 0x80080
	s_addc_u32 s25, s25, 0
	s_add_i32 s26, s66, s31
	s_add_u32 vcc_lo, s24, 0xfff80000
	s_addc_u32 vcc_hi, s25, -1
	global_load_lds_dwordx4 v152, vcc
	s_mov_b32 m0, s26
	s_nop 0
	global_load_lds_dwordx4 v2, s[24:25]
	s_add_i32 m0, s26, 0x2000
	s_nop 0
	global_load_lds_dwordx4 v152, s[24:25]
	v_lshl_add_u64 v[166:167], v[238:239], 0, s[36:37]
	s_mov_b32 m0, s44
	s_nop 0
	global_load_lds_dwordx4 v[166:167], off
	v_lshl_add_u64 v[166:167], v[240:241], 0, s[36:37]
	s_mov_b32 m0, s45
	s_nop 0
	global_load_lds_dwordx4 v[166:167], off
	s_waitcnt vmcnt(8)
	s_waitcnt lgkmcnt(0)
	s_barrier
	s_setprio 1
	s_waitcnt lgkmcnt(0)
	v_mfma_f32_16x16x32_bf16 v[64:67], v[132:135], v[204:207], v[64:67]
	v_mfma_f32_16x16x32_bf16 v[60:63], v[158:161], v[204:207], v[60:63]
	v_mfma_f32_16x16x32_bf16 v[48:51], v[132:135], v[212:215], v[48:51]
	v_mfma_f32_16x16x32_bf16 v[44:47], v[158:161], v[212:215], v[44:47]
	v_mfma_f32_16x16x32_bf16 v[32:35], v[132:135], v[220:223], v[32:35]
	v_mfma_f32_16x16x32_bf16 v[28:31], v[158:161], v[220:223], v[28:31]
	v_mfma_f32_16x16x32_bf16 v[16:19], v[132:135], v[228:231], v[16:19]
	v_mfma_f32_16x16x32_bf16 v[12:15], v[158:161], v[228:231], v[12:15]
	v_mfma_f32_16x16x32_bf16 v[64:67], v[136:139], v[208:211], v[64:67]
	v_mfma_f32_16x16x32_bf16 v[60:63], v[162:165], v[208:211], v[60:63]
	v_mfma_f32_16x16x32_bf16 v[48:51], v[136:139], v[216:219], v[48:51]
	v_mfma_f32_16x16x32_bf16 v[44:47], v[162:165], v[216:219], v[44:47]
	v_mfma_f32_16x16x32_bf16 v[32:35], v[136:139], v[224:227], v[32:35]
	v_mfma_f32_16x16x32_bf16 v[28:31], v[162:165], v[224:227], v[28:31]
	v_mfma_f32_16x16x32_bf16 v[16:19], v[136:139], v[232:235], v[16:19]
	v_mfma_f32_16x16x32_bf16 v[12:15], v[162:165], v[232:235], v[12:15]
	s_setprio 0
	s_setprio 1
	v_mfma_f32_16x16x32_bf16 v[56:59], v[188:191], v[204:207], v[56:59]
	v_mfma_f32_16x16x32_bf16 v[52:55], v[196:199], v[204:207], v[52:55]
	v_mfma_f32_16x16x32_bf16 v[40:43], v[188:191], v[212:215], v[40:43]
	v_mfma_f32_16x16x32_bf16 v[36:39], v[196:199], v[212:215], v[36:39]
	v_mfma_f32_16x16x32_bf16 v[24:27], v[188:191], v[220:223], v[24:27]
	v_mfma_f32_16x16x32_bf16 v[20:23], v[196:199], v[220:223], v[20:23]
	v_mfma_f32_16x16x32_bf16 v[8:11], v[188:191], v[228:231], v[8:11]
	v_mfma_f32_16x16x32_bf16 v[4:7], v[196:199], v[228:231], v[4:7]
	v_mfma_f32_16x16x32_bf16 v[56:59], v[192:195], v[208:211], v[56:59]
	v_mfma_f32_16x16x32_bf16 v[52:55], v[200:203], v[208:211], v[52:55]
	v_mfma_f32_16x16x32_bf16 v[40:43], v[192:195], v[216:219], v[40:43]
	v_mfma_f32_16x16x32_bf16 v[36:39], v[200:203], v[216:219], v[36:39]
	v_mfma_f32_16x16x32_bf16 v[24:27], v[192:195], v[224:227], v[24:27]
	v_mfma_f32_16x16x32_bf16 v[20:23], v[200:203], v[224:227], v[20:23]
	v_mfma_f32_16x16x32_bf16 v[8:11], v[192:195], v[232:235], v[8:11]
	v_mfma_f32_16x16x32_bf16 v[4:7], v[200:203], v[232:235], v[4:7]
	s_setprio 0
	s_barrier
	s_add_i32 s64, s64, 2
	s_add_u32 s22, s22, 0x100
	s_addc_u32 s23, s23, 0
	s_add_u32 s57, s57, 0x100
	s_addc_u32 s63, s63, 0
	s_cmp_gt_u32 s64, 29

; #define PG8_STAGE(bufoff, gbase, voff) do { _Pragma("unroll") for (int _i = 0; _i < 2; ++_i) \
;         __builtin_amdgcn_global_load_lds((const unsigned*)((const char*)(gbase) + (voff)[_i]), (PG8_LAS unsigned*)(lds + (bufoff) + ldsw + _i * 8192), 16, 0, 0); } while (0)
; #define PG8_LDA(dst, b, h) do { _Pragma("unroll") for (int m = 0; m < 4; ++m) _Pragma("unroll") for (int k = 0; k < 2; ++k) dst[m][k] = *(const PG8_LAS bf16x8*)(lds + PG8_SA(b, h) + aoff + m * 2048 + k * 1024); } while (0)
; #define PG8_LDB(dst, b, h) do { _Pragma("unroll") for (int n = 0; n < 2; ++n) _Pragma("unroll") for (int k = 0; k < 2; ++k) dst[n][k] = *(const PG8_LAS bf16x8*)(lds + PG8_SB(b, h) + boff + n * 2048 + k * 1024); } while (0)
; #define PG8_MMA(ai, bj, At, Bt) do { __builtin_amdgcn_s_setprio(1); _Pragma("unroll") for (int m = 0; m < 4; ++m) _Pragma("unroll") for (int n = 0; n < 2; ++n) _Pragma("unroll") for (int k = 0; k < 2; ++k) \
;         acc[ai][bj][m][n] = __builtin_amdgcn_mfma_f32_16x16x32_bf16(Bt[n][k], At[m][k], acc[ai][bj][m][n], 0, 0, 0); __builtin_amdgcn_s_setprio(0); } while (0)
; #define PG8_WAIT_V(n) asm volatile("s_waitcnt vmcnt(" #n ")" ::: "memory")
; template <class Epi, class Sched, bool ALIGN_EPI = false, bool SP2 = false>
; __device__ __forceinline__ void gemm_phase(PG8_LAS unsigned char* lds, const Gemm g, const Sched& S, const Epi& E) {
;     ...
;         const char* nA = has_next ? (const char*)g.A + (size_t)nxt.pm * tstep : cA; const char* nB = has_next ? (const char*)g.Bt + (size_t)nxt.pn * tstep : cB;
;         for (int t = 0; t < nt; t += 2) {
;             const bool last = (t == nt - 2);
;             const char* a1 = cA + (size_t)(t + 1) * kstep;
;             const char* a2 = last ? nA : cA + (size_t)(t + 2) * kstep; const char* b2 = last ? nB : cB + (size_t)(t + 2) * kstep;
;             const char* a3 = a2 + kstep; const char* b3 = b2 + kstep;
;             if (last && has_next) S.a_ready(nxt);
;             if constexpr (SP2) {
;             PG8_LDB(B0, 0, 0); PG8_LDB(B1, 0, 1); PG8_SCHED; PG8_LDA(At, 0, 0); PG8_STAGE(PG8_SA(1, 1), a1 + hstep, voffA);
;             PG8_WAIT_V(8); PG8_WAIT_L(0); PG8_BAR; PG8_MMA(0, 0, At, B0); PG8_MMA(0, 1, At, B1); PG8_BAR; PG8_SCHED;
;             PG8_LDA(At, 0, 1); PG8_STAGE(PG8_SB(0, 0), b2, voffB); PG8_STAGE(PG8_SB(0, 1), b2 + hstep, voffB); PG8_STAGE(PG8_SA(0, 0), a2, voffA);
.LBB0_566:
	s_ashr_i32 s11, s10, 31
	s_lshl_b64 s[12:13], s[10:11], 20
	s_add_u32 s12, s46, s12
	s_addc_u32 s13, s47, s13
	s_and_b64 s[14:15], s[2:3], exec
	s_cselect_b32 s11, s13, s19
	s_cselect_b32 s45, s12, s18
	s_ashr_i32 s9, s8, 31
	s_lshl_b64 s[14:15], s[8:9], 20
	s_add_u32 s14, s25, s14
	s_addc_u32 s15, s26, s15
	s_and_b64 s[22:23], s[2:3], exec
	s_cselect_b32 s9, s15, s21
	s_cselect_b32 s50, s14, s20
	s_add_u32 s18, s18, 0x80080
	s_addc_u32 s19, s19, 0
	s_add_u32 s51, s20, 0x100
	s_addc_u32 s56, s21, 0
	s_mov_b32 s57, -2
	s_add_u32 s20, s18, 0xfff80080
	s_addc_u32 s21, s19, -1
	s_add_i32 s63, 0, 0x10000
	s_cmp_eq_u32 s57, 28
	s_cselect_b32 s23, s11, s21
	s_cselect_b32 s22, s45, s20
	v_add_u32_e32 v150, s63, v153
	s_cselect_b32 s21, s9, s56
	s_cselect_b32 s20, s50, s51
	s_add_i32 s66, 0, 0x14000
	ds_read_b128 v[184:187], v150
	ds_read_b128 v[188:191], v150 offset:1024
	ds_read_b128 v[192:195], v150 offset:2048
	ds_read_b128 v[196:199], v150 offset:3072
	v_add_u32_e32 v150, s66, v153
	ds_read_b128 v[200:203], v150
	ds_read_b128 v[204:207], v150 offset:1024
	ds_read_b128 v[208:211], v150 offset:2048
	ds_read_b128 v[212:215], v150 offset:3072
	s_add_i32 m0, s29, 0xc000
	ds_read_b128 v[216:219], v155
	ds_read_b128 v[220:223], v155 offset:1024
	ds_read_b128 v[224:227], v155 offset:2048
	ds_read_b128 v[228:231], v155 offset:3072
	ds_read_b128 v[232:235], v155 offset:4096
	ds_read_b128 v[236:239], v155 offset:5120
	ds_read_b128 v[240:243], v155 offset:6144
	ds_read_b128 v[244:247], v155 offset:7168
	global_load_lds_dwordx4 v136, s[18:19]
	s_add_i32 m0, s29, 0xe000
	s_nop 0
	global_load_lds_dwordx4 v138, s[18:19]
	s_waitcnt vmcnt(8)
	s_waitcnt lgkmcnt(0)
	s_barrier
	s_setprio 1
	s_waitcnt lgkmcnt(0)
	v_mfma_f32_16x16x32_bf16 v[128:131], v[184:187], v[216:219], 0
	v_mfma_f32_16x16x32_bf16 v[120:123], v[192:195], v[216:219], 0
	v_mfma_f32_16x16x32_bf16 v[112:115], v[184:187], v[224:227], 0
	v_mfma_f32_16x16x32_bf16 v[104:107], v[192:195], v[224:227], 0
	v_mfma_f32_16x16x32_bf16 v[96:99], v[184:187], v[232:235], 0
	v_mfma_f32_16x16x32_bf16 v[88:91], v[192:195], v[232:235], 0
	v_mfma_f32_16x16x32_bf16 v[80:83], v[184:187], v[240:243], 0
	v_mfma_f32_16x16x32_bf16 v[72:75], v[192:195], v[240:243], 0
	v_mfma_f32_16x16x32_bf16 v[128:131], v[188:191], v[220:223], v[128:131]
	v_mfma_f32_16x16x32_bf16 v[120:123], v[196:199], v[220:223], v[120:123]
	v_mfma_f32_16x16x32_bf16 v[112:115], v[188:191], v[228:231], v[112:115]
	v_mfma_f32_16x16x32_bf16 v[104:107], v[196:199], v[228:231], v[104:107]
	v_mfma_f32_16x16x32_bf16 v[96:99], v[188:191], v[236:239], v[96:99]
	v_mfma_f32_16x16x32_bf16 v[88:91], v[196:199], v[236:239], v[88:91]
	v_mfma_f32_16x16x32_bf16 v[80:83], v[188:191], v[244:247], v[80:83]
	v_mfma_f32_16x16x32_bf16 v[72:75], v[196:199], v[244:247], v[72:75]
	s_setprio 0
	s_setprio 1
	v_mfma_f32_16x16x32_bf16 v[124:127], v[200:203], v[216:219], 0
	v_mfma_f32_16x16x32_bf16 v[116:119], v[208:211], v[216:219], 0
	v_mfma_f32_16x16x32_bf16 v[108:111], v[200:203], v[224:227], 0
	v_mfma_f32_16x16x32_bf16 v[100:103], v[208:211], v[224:227], 0
	v_mfma_f32_16x16x32_bf16 v[92:95], v[200:203], v[232:235], 0
	v_mfma_f32_16x16x32_bf16 v[84:87], v[208:211], v[232:235], 0
	v_mfma_f32_16x16x32_bf16 v[76:79], v[200:203], v[240:243], 0
	v_mfma_f32_16x16x32_bf16 v[68:71], v[208:211], v[240:243], 0
	v_mfma_f32_16x16x32_bf16 v[124:127], v[204:207], v[220:223], v[124:127]
	v_mfma_f32_16x16x32_bf16 v[116:119], v[212:215], v[220:223], v[116:119]
	v_mfma_f32_16x16x32_bf16 v[108:111], v[204:207], v[228:231], v[108:111]
	v_mfma_f32_16x16x32_bf16 v[100:103], v[212:215], v[228:231], v[100:103]
	v_mfma_f32_16x16x32_bf16 v[92:95], v[204:207], v[236:239], v[92:95]
	v_mfma_f32_16x16x32_bf16 v[84:87], v[212:215], v[236:239], v[84:87]
	v_mfma_f32_16x16x32_bf16 v[76:79], v[204:207], v[244:247], v[76:79]
	v_mfma_f32_16x16x32_bf16 v[68:71], v[212:215], v[244:247], v[68:71]
	s_setprio 0
	s_barrier
	s_add_i32 s63, s63, s27
	s_mov_b32 m0, s63
	ds_read_b128 v[216:219], v155 offset:16384
	ds_read_b128 v[220:223], v155 offset:17408
	ds_read_b128 v[224:227], v155 offset:18432
	ds_read_b128 v[228:231], v155 offset:19456
	ds_read_b128 v[232:235], v155 offset:20480
	ds_read_b128 v[236:239], v155 offset:21504
	ds_read_b128 v[240:243], v155 offset:22528
	ds_read_b128 v[244:247], v155 offset:23552
	global_load_lds_dwordx4 v2, s[20:21]
	s_add_i32 m0, s63, 0x2000
	s_add_u32 s64, s20, 0x80000
	s_addc_u32 s65, s21, 0
	s_add_i32 s63, s66, s27
	global_load_lds_dwordx4 v0, s[20:21]
	s_mov_b32 m0, s63
	v_lshl_add_u64 v[250:251], s[22:23], 0, v[132:133]
	global_load_lds_dwordx4 v2, s[64:65]
	s_add_i32 m0, s63, 0x2000
	s_nop 0
	global_load_lds_dwordx4 v0, s[64:65]
	v_lshl_add_u64 v[248:249], s[22:23], 0, v[134:135]
	s_mov_b32 m0, s29
	s_nop 0
	global_load_lds_dwordx4 v[248:249], off
	s_mov_b32 m0, s30
	s_nop 0
	global_load_lds_dwordx4 v[250:251], off
	s_waitcnt vmcnt(8)
	s_waitcnt lgkmcnt(0)
	s_barrier
; #define PG8_STAGE(bufoff, gbase, voff) do { _Pragma("unroll") for (int _i = 0; _i < 2; ++_i) \
;         __builtin_amdgcn_global_load_lds((const unsigned*)((const char*)(gbase) + (voff)[_i]), (PG8_LAS unsigned*)(lds + (bufoff) + ldsw + _i * 8192), 16, 0, 0); } while (0)
; #define PG8_LDA(dst, b, h) do { _Pragma("unroll") for (int m = 0; m < 4; ++m) _Pragma("unroll") for (int k = 0; k < 2; ++k) dst[m][k] = *(const PG8_LAS bf16x8*)(lds + PG8_SA(b, h) + aoff + m * 2048 + k * 1024); } while (0)
; #define PG8_LDB(dst, b, h) do { _Pragma("unroll") for (int n = 0; n < 2; ++n) _Pragma("unroll") for (int k = 0; k < 2; ++k) dst[n][k] = *(const PG8_LAS bf16x8*)(lds + PG8_SB(b, h) + boff + n * 2048 + k * 1024); } while (0)
; #define PG8_MMA(ai, bj, At, Bt) do { __builtin_amdgcn_s_setprio(1); _Pragma("unroll") for (int m = 0; m < 4; ++m) _Pragma("unroll") for (int n = 0; n < 2; ++n) _Pragma("unroll") for (int k = 0; k < 2; ++k) \
;         acc[ai][bj][m][n] = __builtin_amdgcn_mfma_f32_16x16x32_bf16(Bt[n][k], At[m][k], acc[ai][bj][m][n], 0, 0, 0); __builtin_amdgcn_s_setprio(0); } while (0)
; #define PG8_WAIT_V(n) asm volatile("s_waitcnt vmcnt(" #n ")" ::: "memory")
; #define PG8_WAIT_L(n) asm volatile("s_waitcnt lgkmcnt(" #n ")" ::: "memory")
; #define PG8_BAR __builtin_amdgcn_s_barrier()
; #define PG8_SCHED __builtin_amdgcn_sched_barrier(0)
; template <class Epi, class Sched, bool ALIGN_EPI = false, bool SP2 = false>
; __device__ __forceinline__ void gemm_phase(PG8_LAS unsigned char* lds, const Gemm g, const Sched& S, const Epi& E) {
;     ...
;             PG8_WAIT_V(8); PG8_WAIT_L(0); PG8_BAR; PG8_MMA(1, 0, At, B0); PG8_MMA(1, 1, At, B1); PG8_BAR; PG8_SCHED;
;             PG8_LDB(B0, 1, 0); PG8_LDB(B1, 1, 1); PG8_SCHED; PG8_LDA(At, 1, 0); PG8_STAGE(PG8_SA(0, 1), a2 + hstep, voffA);
;             PG8_WAIT_V(8); PG8_WAIT_L(0); PG8_BAR; PG8_MMA(0, 0, At, B0); PG8_MMA(0, 1, At, B1); PG8_BAR; PG8_SCHED;
	s_setprio 1
	s_waitcnt lgkmcnt(0)
	v_mfma_f32_16x16x32_bf16 v[64:67], v[184:187], v[216:219], 0
	v_mfma_f32_16x16x32_bf16 v[56:59], v[192:195], v[216:219], 0
	v_mfma_f32_16x16x32_bf16 v[48:51], v[184:187], v[224:227], 0
	v_mfma_f32_16x16x32_bf16 v[40:43], v[192:195], v[224:227], 0
	v_mfma_f32_16x16x32_bf16 v[32:35], v[184:187], v[232:235], 0
	v_mfma_f32_16x16x32_bf16 v[24:27], v[192:195], v[232:235], 0
	v_mfma_f32_16x16x32_bf16 v[16:19], v[184:187], v[240:243], 0
	v_mfma_f32_16x16x32_bf16 v[8:11], v[192:195], v[240:243], 0
	v_mfma_f32_16x16x32_bf16 v[64:67], v[188:191], v[220:223], v[64:67]
	v_mfma_f32_16x16x32_bf16 v[56:59], v[196:199], v[220:223], v[56:59]
	v_mfma_f32_16x16x32_bf16 v[48:51], v[188:191], v[228:231], v[48:51]
	v_mfma_f32_16x16x32_bf16 v[40:43], v[196:199], v[228:231], v[40:43]
	v_mfma_f32_16x16x32_bf16 v[32:35], v[188:191], v[236:239], v[32:35]
	v_mfma_f32_16x16x32_bf16 v[24:27], v[196:199], v[236:239], v[24:27]
	v_mfma_f32_16x16x32_bf16 v[16:19], v[188:191], v[244:247], v[16:19]
	v_mfma_f32_16x16x32_bf16 v[8:11], v[196:199], v[244:247], v[8:11]
	s_setprio 0
	s_setprio 1
	v_mfma_f32_16x16x32_bf16 v[60:63], v[200:203], v[216:219], 0
	v_mfma_f32_16x16x32_bf16 v[52:55], v[208:211], v[216:219], 0
	v_mfma_f32_16x16x32_bf16 v[44:47], v[200:203], v[224:227], 0
	v_mfma_f32_16x16x32_bf16 v[36:39], v[208:211], v[224:227], 0
	v_mfma_f32_16x16x32_bf16 v[28:31], v[200:203], v[232:235], 0
	v_mfma_f32_16x16x32_bf16 v[20:23], v[208:211], v[232:235], 0
	v_mfma_f32_16x16x32_bf16 v[12:15], v[200:203], v[240:243], 0
	v_mfma_f32_16x16x32_bf16 v[4:7], v[208:211], v[240:243], 0
	v_mfma_f32_16x16x32_bf16 v[60:63], v[204:207], v[220:223], v[60:63]
	v_mfma_f32_16x16x32_bf16 v[52:55], v[212:215], v[220:223], v[52:55]
	v_mfma_f32_16x16x32_bf16 v[44:47], v[204:207], v[228:231], v[44:47]
	v_mfma_f32_16x16x32_bf16 v[36:39], v[212:215], v[228:231], v[36:39]
	v_mfma_f32_16x16x32_bf16 v[28:31], v[204:207], v[236:239], v[28:31]
	v_mfma_f32_16x16x32_bf16 v[20:23], v[212:215], v[236:239], v[20:23]
	v_mfma_f32_16x16x32_bf16 v[12:15], v[204:207], v[244:247], v[12:15]
	v_mfma_f32_16x16x32_bf16 v[4:7], v[212:215], v[244:247], v[4:7]
	s_setprio 0
	s_barrier
	s_add_i32 s63, 0, 0x18000
	v_add_u32_e32 v161, s63, v153
	s_add_i32 s64, 0, 0x1c000
	ds_read_b128 v[184:187], v161
	ds_read_b128 v[188:191], v161 offset:1024
	ds_read_b128 v[192:195], v161 offset:2048
	ds_read_b128 v[196:199], v161 offset:3072
	v_add_u32_e32 v161, s64, v153
	ds_read_b128 v[200:203], v161
	ds_read_b128 v[204:207], v161 offset:1024
	ds_read_b128 v[208:211], v161 offset:2048
	ds_read_b128 v[212:215], v161 offset:3072
	s_add_u32 s22, s22, 0x80000
	s_addc_u32 s23, s23, 0
	s_mov_b32 m0, s31
	ds_read_b128 v[216:219], v155 offset:32768
	ds_read_b128 v[220:223], v155 offset:33792
	ds_read_b128 v[224:227], v155 offset:34816
	ds_read_b128 v[228:231], v155 offset:35840
	ds_read_b128 v[232:235], v155 offset:36864
	ds_read_b128 v[236:239], v155 offset:37888
	ds_read_b128 v[240:243], v155 offset:38912
	ds_read_b128 v[244:247], v155 offset:39936
	global_load_lds_dwordx4 v134, s[22:23]
	s_mov_b32 m0, s34
	s_nop 0
	global_load_lds_dwordx4 v132, s[22:23]
	s_waitcnt vmcnt(8)
	s_waitcnt lgkmcnt(0)
	s_barrier
	s_setprio 1
	s_waitcnt lgkmcnt(0)
	v_mfma_f32_16x16x32_bf16 v[128:131], v[184:187], v[216:219], v[128:131]
	v_mfma_f32_16x16x32_bf16 v[120:123], v[192:195], v[216:219], v[120:123]
	v_mfma_f32_16x16x32_bf16 v[112:115], v[184:187], v[224:227], v[112:115]
	v_mfma_f32_16x16x32_bf16 v[104:107], v[192:195], v[224:227], v[104:107]
	v_mfma_f32_16x16x32_bf16 v[96:99], v[184:187], v[232:235], v[96:99]
	v_mfma_f32_16x16x32_bf16 v[88:91], v[192:195], v[232:235], v[88:91]
	v_mfma_f32_16x16x32_bf16 v[80:83], v[184:187], v[240:243], v[80:83]
	v_mfma_f32_16x16x32_bf16 v[72:75], v[192:195], v[240:243], v[72:75]
	v_mfma_f32_16x16x32_bf16 v[128:131], v[188:191], v[220:223], v[128:131]
	v_mfma_f32_16x16x32_bf16 v[120:123], v[196:199], v[220:223], v[120:123]
	v_mfma_f32_16x16x32_bf16 v[112:115], v[188:191], v[228:231], v[112:115]
	v_mfma_f32_16x16x32_bf16 v[104:107], v[196:199], v[228:231], v[104:107]
	v_mfma_f32_16x16x32_bf16 v[96:99], v[188:191], v[236:239], v[96:99]
	v_mfma_f32_16x16x32_bf16 v[88:91], v[196:199], v[236:239], v[88:91]
	v_mfma_f32_16x16x32_bf16 v[80:83], v[188:191], v[244:247], v[80:83]
	v_mfma_f32_16x16x32_bf16 v[72:75], v[196:199], v[244:247], v[72:75]
	s_setprio 0
	s_setprio 1
	v_mfma_f32_16x16x32_bf16 v[124:127], v[200:203], v[216:219], v[124:127]
	v_mfma_f32_16x16x32_bf16 v[116:119], v[208:211], v[216:219], v[116:119]
	v_mfma_f32_16x16x32_bf16 v[108:111], v[200:203], v[224:227], v[108:111]
	v_mfma_f32_16x16x32_bf16 v[100:103], v[208:211], v[224:227], v[100:103]
	v_mfma_f32_16x16x32_bf16 v[92:95], v[200:203], v[232:235], v[92:95]
	v_mfma_f32_16x16x32_bf16 v[84:87], v[208:211], v[232:235], v[84:87]
	v_mfma_f32_16x16x32_bf16 v[76:79], v[200:203], v[240:243], v[76:79]
	v_mfma_f32_16x16x32_bf16 v[68:71], v[208:211], v[240:243], v[68:71]
	v_mfma_f32_16x16x32_bf16 v[124:127], v[204:207], v[220:223], v[124:127]
	v_mfma_f32_16x16x32_bf16 v[116:119], v[212:215], v[220:223], v[116:119]
	v_mfma_f32_16x16x32_bf16 v[108:111], v[204:207], v[228:231], v[108:111]
	v_mfma_f32_16x16x32_bf16 v[100:103], v[212:215], v[228:231], v[100:103]
	v_mfma_f32_16x16x32_bf16 v[92:95], v[204:207], v[236:239], v[92:95]
	v_mfma_f32_16x16x32_bf16 v[84:87], v[212:215], v[236:239], v[84:87]
	v_mfma_f32_16x16x32_bf16 v[76:79], v[204:207], v[244:247], v[76:79]
	v_mfma_f32_16x16x32_bf16 v[68:71], v[212:215], v[244:247], v[68:71]
	s_setprio 0
	s_barrier
; #define PG8_STAGE(bufoff, gbase, voff) do { _Pragma("unroll") for (int _i = 0; _i < 2; ++_i) \
;         __builtin_amdgcn_global_load_lds((const unsigned*)((const char*)(gbase) + (voff)[_i]), (PG8_LAS unsigned*)(lds + (bufoff) + ldsw + _i * 8192), 16, 0, 0); } while (0)
; #define PG8_LDA(dst, b, h) do { _Pragma("unroll") for (int m = 0; m < 4; ++m) _Pragma("unroll") for (int k = 0; k < 2; ++k) dst[m][k] = *(const PG8_LAS bf16x8*)(lds + PG8_SA(b, h) + aoff + m * 2048 + k * 1024); } while (0)
; #define PG8_MMA(ai, bj, At, Bt) do { __builtin_amdgcn_s_setprio(1); _Pragma("unroll") for (int m = 0; m < 4; ++m) _Pragma("unroll") for (int n = 0; n < 2; ++n) _Pragma("unroll") for (int k = 0; k < 2; ++k) \
;         acc[ai][bj][m][n] = __builtin_amdgcn_mfma_f32_16x16x32_bf16(Bt[n][k], At[m][k], acc[ai][bj][m][n], 0, 0, 0); __builtin_amdgcn_s_setprio(0); } while (0)
; #define PG8_WAIT_V(n) asm volatile("s_waitcnt vmcnt(" #n ")" ::: "memory")
; #define PG8_WAIT_L(n) asm volatile("s_waitcnt lgkmcnt(" #n ")" ::: "memory")
; #define PG8_BAR __builtin_amdgcn_s_barrier()
; #define PG8_SCHED __builtin_amdgcn_sched_barrier(0)
; template <class Epi, class Sched, bool ALIGN_EPI = false, bool SP2 = false>
; __device__ __forceinline__ void gemm_phase(PG8_LAS unsigned char* lds, const Gemm g, const Sched& S, const Epi& E) {
;     ...
;             PG8_LDA(At, 1, 1); PG8_STAGE(PG8_SB(1, 0), b3, voffB); PG8_STAGE(PG8_SB(1, 1), b3 + hstep, voffB); PG8_STAGE(PG8_SA(1, 0), a3, voffA);
;             PG8_WAIT_V(8); PG8_WAIT_L(0); PG8_BAR; PG8_MMA(1, 0, At, B0); PG8_MMA(1, 1, At, B1); PG8_BAR; PG8_SCHED;
	s_add_i32 s22, s63, s27
	s_mov_b32 m0, s22
	ds_read_b128 v[216:219], v155 offset:49152
	ds_read_b128 v[220:223], v155 offset:50176
	ds_read_b128 v[224:227], v155 offset:51200
	ds_read_b128 v[228:231], v155 offset:52224
	ds_read_b128 v[232:235], v155 offset:53248
	ds_read_b128 v[236:239], v155 offset:54272
	ds_read_b128 v[240:243], v155 offset:55296
	ds_read_b128 v[244:247], v155 offset:56320
	s_add_u32 vcc_lo, s20, 0x80
	s_addc_u32 vcc_hi, s21, 0
	global_load_lds_dwordx4 v2, vcc
	s_add_i32 m0, s22, 0x2000
	s_add_u32 s20, s20, 0x80080
	s_addc_u32 s21, s21, 0
	s_add_i32 s22, s64, s27
	s_add_u32 vcc_lo, s20, 0xfff80000
	s_addc_u32 vcc_hi, s21, -1
	global_load_lds_dwordx4 v0, vcc
	s_mov_b32 m0, s22
	s_nop 0
	global_load_lds_dwordx4 v2, s[20:21]
	s_add_i32 m0, s22, 0x2000
	s_nop 0
	global_load_lds_dwordx4 v0, s[20:21]
	v_lshl_add_u64 v[150:151], v[248:249], 0, s[36:37]
	s_mov_b32 m0, s35
	s_nop 0
	global_load_lds_dwordx4 v[150:151], off
	v_lshl_add_u64 v[150:151], v[250:251], 0, s[36:37]
	s_mov_b32 m0, s42
	s_nop 0
	global_load_lds_dwordx4 v[150:151], off
	s_waitcnt vmcnt(8)
	s_waitcnt lgkmcnt(0)
	s_barrier
	s_setprio 1
	s_waitcnt lgkmcnt(0)
	v_mfma_f32_16x16x32_bf16 v[64:67], v[184:187], v[216:219], v[64:67]
	v_mfma_f32_16x16x32_bf16 v[56:59], v[192:195], v[216:219], v[56:59]
	v_mfma_f32_16x16x32_bf16 v[48:51], v[184:187], v[224:227], v[48:51]
	v_mfma_f32_16x16x32_bf16 v[40:43], v[192:195], v[224:227], v[40:43]
	v_mfma_f32_16x16x32_bf16 v[32:35], v[184:187], v[232:235], v[32:35]
	v_mfma_f32_16x16x32_bf16 v[24:27], v[192:195], v[232:235], v[24:27]
	v_mfma_f32_16x16x32_bf16 v[16:19], v[184:187], v[240:243], v[16:19]
	v_mfma_f32_16x16x32_bf16 v[8:11], v[192:195], v[240:243], v[8:11]
	v_mfma_f32_16x16x32_bf16 v[64:67], v[188:191], v[220:223], v[64:67]
	v_mfma_f32_16x16x32_bf16 v[56:59], v[196:199], v[220:223], v[56:59]
	v_mfma_f32_16x16x32_bf16 v[48:51], v[188:191], v[228:231], v[48:51]
	v_mfma_f32_16x16x32_bf16 v[40:43], v[196:199], v[228:231], v[40:43]
	v_mfma_f32_16x16x32_bf16 v[32:35], v[188:191], v[236:239], v[32:35]
	v_mfma_f32_16x16x32_bf16 v[24:27], v[196:199], v[236:239], v[24:27]
	v_mfma_f32_16x16x32_bf16 v[16:19], v[188:191], v[244:247], v[16:19]
	v_mfma_f32_16x16x32_bf16 v[8:11], v[196:199], v[244:247], v[8:11]
	s_setprio 0
	s_setprio 1
	v_mfma_f32_16x16x32_bf16 v[60:63], v[200:203], v[216:219], v[60:63]
	v_mfma_f32_16x16x32_bf16 v[52:55], v[208:211], v[216:219], v[52:55]
	v_mfma_f32_16x16x32_bf16 v[44:47], v[200:203], v[224:227], v[44:47]
	v_mfma_f32_16x16x32_bf16 v[36:39], v[208:211], v[224:227], v[36:39]
	v_mfma_f32_16x16x32_bf16 v[28:31], v[200:203], v[232:235], v[28:31]
	v_mfma_f32_16x16x32_bf16 v[20:23], v[208:211], v[232:235], v[20:23]
	v_mfma_f32_16x16x32_bf16 v[12:15], v[200:203], v[240:243], v[12:15]
	v_mfma_f32_16x16x32_bf16 v[4:7], v[208:211], v[240:243], v[4:7]
	v_mfma_f32_16x16x32_bf16 v[60:63], v[204:207], v[220:223], v[60:63]
	v_mfma_f32_16x16x32_bf16 v[52:55], v[212:215], v[220:223], v[52:55]
	v_mfma_f32_16x16x32_bf16 v[44:47], v[204:207], v[228:231], v[44:47]
	v_mfma_f32_16x16x32_bf16 v[36:39], v[212:215], v[228:231], v[36:39]
	v_mfma_f32_16x16x32_bf16 v[28:31], v[204:207], v[236:239], v[28:31]
	v_mfma_f32_16x16x32_bf16 v[20:23], v[212:215], v[236:239], v[20:23]
	v_mfma_f32_16x16x32_bf16 v[12:15], v[204:207], v[244:247], v[12:15]
	v_mfma_f32_16x16x32_bf16 v[4:7], v[212:215], v[244:247], v[4:7]
	s_setprio 0
	s_barrier
	s_add_i32 s57, s57, 2
	s_add_u32 s18, s18, 0x100
	s_addc_u32 s19, s19, 0
	s_add_u32 s51, s51, 0x100
	s_addc_u32 s56, s56, 0
	s_cmp_gt_u32 s57, 29
